# snake MFMA order grouped by B fragment (srcA) instead of A fragment: chain C, share B within group, share A across groups
# baseline (speedup 1.0000x reference)
.LBB0_256:
	v_add_u32_e32 v172, s70, v160
	v_add_u32_e32 v188, s71, v160
	ds_read_b128 v[154:157], v172
	ds_read_b128 v[164:167], v172 offset:1024
	ds_read_b128 v[168:171], v172 offset:2048
	ds_read_b128 v[172:175], v172 offset:3072
	ds_read_b128 v[176:179], v188
	ds_read_b128 v[180:183], v188 offset:1024
	ds_read_b128 v[184:187], v188 offset:2048
	ds_read_b128 v[188:191], v188 offset:3072
	s_add_i32 s75, s30, 2
	s_add_u32 s31, s28, 0xfffc0080
	s_addc_u32 s34, s29, -1
	s_cmp_eq_u32 s67, s30
	s_cselect_b32 s30, s26, s17
	s_cselect_b32 s35, s25, s34
	s_cselect_b32 s34, s24, s31
	s_cselect_b32 s31, s27, s19
	v_lshl_add_u64 v[224:225], s[28:29], 0, v[146:147]
	s_add_i32 m0, s58, 0xc000
	ds_read_b128 v[192:195], v163
	ds_read_b128 v[196:199], v163 offset:1024
	ds_read_b128 v[200:203], v163 offset:2048
	ds_read_b128 v[204:207], v163 offset:3072
	ds_read_b128 v[208:211], v163 offset:4096
	ds_read_b128 v[212:215], v163 offset:5120
	ds_read_b128 v[216:219], v163 offset:6144
	ds_read_b128 v[220:223], v163 offset:7168
	global_load_lds_dwordx4 v[224:225], off
	v_lshl_add_u64 v[224:225], s[28:29], 0, v[148:149]
	s_add_i32 m0, s58, 0xe000
	s_nop 0
	global_load_lds_dwordx4 v[224:225], off
	s_waitcnt vmcnt(8)
	s_waitcnt lgkmcnt(0)
	s_barrier
	v_mfma_f32_16x16x32_bf16 v[42:45], v[154:157], v[192:195], v[42:45]
	v_mfma_f32_16x16x32_bf16 v[42:45], v[164:167], v[196:199], v[42:45]
	v_mfma_f32_16x16x32_bf16 v[54:57], v[164:167], v[204:207], v[54:57]
	v_mfma_f32_16x16x32_bf16 v[54:57], v[154:157], v[200:203], v[54:57]
	v_mfma_f32_16x16x32_bf16 v[66:69], v[154:157], v[208:211], v[66:69]
	v_mfma_f32_16x16x32_bf16 v[66:69], v[164:167], v[212:215], v[66:69]
	v_mfma_f32_16x16x32_bf16 v[62:65], v[164:167], v[220:223], v[62:65]
	v_mfma_f32_16x16x32_bf16 v[62:65], v[154:157], v[216:219], v[62:65]
	v_mfma_f32_16x16x32_bf16 v[46:49], v[168:171], v[216:219], v[46:49]
	v_mfma_f32_16x16x32_bf16 v[46:49], v[172:175], v[220:223], v[46:49]
	v_mfma_f32_16x16x32_bf16 v[50:53], v[172:175], v[212:215], v[50:53]
	v_mfma_f32_16x16x32_bf16 v[50:53], v[168:171], v[208:211], v[50:53]
	v_mfma_f32_16x16x32_bf16 v[38:41], v[168:171], v[200:203], v[38:41]
	v_mfma_f32_16x16x32_bf16 v[38:41], v[172:175], v[204:207], v[38:41]
	v_mfma_f32_16x16x32_bf16 v[26:29], v[172:175], v[196:199], v[26:29]
	v_mfma_f32_16x16x32_bf16 v[26:29], v[168:171], v[192:195], v[26:29]
	v_mfma_f32_16x16x32_bf16 v[14:17], v[176:179], v[192:195], v[14:17]
	v_mfma_f32_16x16x32_bf16 v[14:17], v[180:183], v[196:199], v[14:17]
	v_mfma_f32_16x16x32_bf16 v[22:25], v[180:183], v[204:207], v[22:25]
	v_mfma_f32_16x16x32_bf16 v[22:25], v[176:179], v[200:203], v[22:25]
	v_mfma_f32_16x16x32_bf16 v[30:33], v[176:179], v[208:211], v[30:33]
	v_mfma_f32_16x16x32_bf16 v[30:33], v[180:183], v[212:215], v[30:33]
	v_mfma_f32_16x16x32_bf16 v[34:37], v[180:183], v[220:223], v[34:37]
	v_mfma_f32_16x16x32_bf16 v[34:37], v[176:179], v[216:219], v[34:37]
	v_mfma_f32_16x16x32_bf16 v[18:21], v[184:187], v[216:219], v[18:21]
	v_mfma_f32_16x16x32_bf16 v[18:21], v[188:191], v[220:223], v[18:21]
	v_mfma_f32_16x16x32_bf16 v[10:13], v[188:191], v[212:215], v[10:13]
	v_mfma_f32_16x16x32_bf16 v[10:13], v[184:187], v[208:211], v[10:13]
	v_mfma_f32_16x16x32_bf16 v[6:9], v[184:187], v[200:203], v[6:9]
	v_mfma_f32_16x16x32_bf16 v[6:9], v[188:191], v[204:207], v[6:9]
	v_mfma_f32_16x16x32_bf16 v[2:5], v[188:191], v[196:199], v[2:5]
	v_mfma_f32_16x16x32_bf16 v[2:5], v[184:187], v[192:195], v[2:5]
	s_barrier
	s_add_i32 s50, s70, s54
	v_lshl_add_u64 v[224:225], s[30:31], 0, v[134:135]
	s_mov_b32 m0, s50
	ds_read_b128 v[192:195], v163 offset:16384
	ds_read_b128 v[196:199], v163 offset:17408
	ds_read_b128 v[200:203], v163 offset:18432
	ds_read_b128 v[204:207], v163 offset:19456
	ds_read_b128 v[208:211], v163 offset:20480
	ds_read_b128 v[212:215], v163 offset:21504
	ds_read_b128 v[216:219], v163 offset:22528
	ds_read_b128 v[220:223], v163 offset:23552
	global_load_lds_dwordx4 v[224:225], off
	s_add_i32 m0, s50, 0x2000
	s_add_u32 s76, s30, 0x40000
	v_lshl_add_u64 v[226:227], s[30:31], 0, v[130:131]
	s_addc_u32 s77, s31, 0
	s_add_i32 s50, s71, s54
	global_load_lds_dwordx4 v[226:227], off
	v_lshl_add_u64 v[228:229], s[76:77], 0, v[134:135]
	s_mov_b32 m0, s50
	v_lshl_add_u64 v[230:231], s[34:35], 0, v[132:133]
	global_load_lds_dwordx4 v[228:229], off
	v_lshl_add_u64 v[228:229], s[76:77], 0, v[130:131]
	s_add_i32 m0, s50, 0x2000
	s_nop 0
	global_load_lds_dwordx4 v[228:229], off
	v_lshl_add_u64 v[228:229], s[34:35], 0, v[136:137]
	s_mov_b32 m0, s58
	s_nop 0
	global_load_lds_dwordx4 v[228:229], off
	s_mov_b32 m0, s59
	s_nop 0
	global_load_lds_dwordx4 v[230:231], off
	s_waitcnt vmcnt(8)
	s_waitcnt lgkmcnt(0)
	s_barrier
	v_mfma_f32_16x16x32_bf16 v[110:113], v[154:157], v[192:195], v[110:113]
	v_mfma_f32_16x16x32_bf16 v[110:113], v[164:167], v[196:199], v[110:113]
	v_mfma_f32_16x16x32_bf16 v[106:109], v[164:167], v[204:207], v[106:109]
	v_mfma_f32_16x16x32_bf16 v[106:109], v[154:157], v[200:203], v[106:109]
	v_mfma_f32_16x16x32_bf16 v[118:121], v[154:157], v[208:211], v[118:121]
	v_mfma_f32_16x16x32_bf16 v[118:121], v[164:167], v[212:215], v[118:121]
	v_mfma_f32_16x16x32_bf16 v[126:129], v[164:167], v[220:223], v[126:129]
	v_mfma_f32_16x16x32_bf16 v[126:129], v[154:157], v[216:219], v[126:129]
	v_mfma_f32_16x16x32_bf16 v[102:105], v[168:171], v[216:219], v[102:105]
	v_mfma_f32_16x16x32_bf16 v[102:105], v[172:175], v[220:223], v[102:105]
	v_mfma_f32_16x16x32_bf16 v[94:97], v[172:175], v[212:215], v[94:97]
	v_mfma_f32_16x16x32_bf16 v[94:97], v[168:171], v[208:211], v[94:97]
	v_mfma_f32_16x16x32_bf16 v[82:85], v[168:171], v[200:203], v[82:85]
	v_mfma_f32_16x16x32_bf16 v[82:85], v[172:175], v[204:207], v[82:85]
	v_mfma_f32_16x16x32_bf16 v[86:89], v[172:175], v[196:199], v[86:89]
	v_mfma_f32_16x16x32_bf16 v[86:89], v[168:171], v[192:195], v[86:89]
	v_mfma_f32_16x16x32_bf16 v[70:73], v[176:179], v[192:195], v[70:73]
	v_mfma_f32_16x16x32_bf16 v[70:73], v[180:183], v[196:199], v[70:73]
	v_mfma_f32_16x16x32_bf16 v[74:77], v[180:183], v[204:207], v[74:77]
	v_mfma_f32_16x16x32_bf16 v[74:77], v[176:179], v[200:203], v[74:77]
	v_mfma_f32_16x16x32_bf16 v[114:117], v[176:179], v[208:211], v[114:117]
	v_mfma_f32_16x16x32_bf16 v[114:117], v[180:183], v[212:215], v[114:117]
	v_mfma_f32_16x16x32_bf16 v[122:125], v[180:183], v[220:223], v[122:125]
	v_mfma_f32_16x16x32_bf16 v[122:125], v[176:179], v[216:219], v[122:125]
	v_mfma_f32_16x16x32_bf16 v[98:101], v[184:187], v[216:219], v[98:101]
	v_mfma_f32_16x16x32_bf16 v[98:101], v[188:191], v[220:223], v[98:101]
	v_mfma_f32_16x16x32_bf16 v[90:93], v[188:191], v[212:215], v[90:93]
	v_mfma_f32_16x16x32_bf16 v[90:93], v[184:187], v[208:211], v[90:93]
	v_mfma_f32_16x16x32_bf16 v[78:81], v[184:187], v[200:203], v[78:81]
	v_mfma_f32_16x16x32_bf16 v[78:81], v[188:191], v[204:207], v[78:81]
	v_mfma_f32_16x16x32_bf16 v[58:61], v[188:191], v[196:199], v[58:61]
	v_mfma_f32_16x16x32_bf16 v[58:61], v[184:187], v[192:195], v[58:61]
	s_barrier
	s_add_i32 s50, 0, 0x18000
	s_add_i32 s51, 0, 0x1c000
	v_add_u32_e32 v172, s50, v160
	v_add_u32_e32 v188, s51, v160
	ds_read_b128 v[154:157], v172
	ds_read_b128 v[164:167], v172 offset:1024
	ds_read_b128 v[168:171], v172 offset:2048
	ds_read_b128 v[172:175], v172 offset:3072
	ds_read_b128 v[176:179], v188
	ds_read_b128 v[180:183], v188 offset:1024
	ds_read_b128 v[184:187], v188 offset:2048
	ds_read_b128 v[188:191], v188 offset:3072
	s_add_u32 s34, s34, 0x40000
	s_addc_u32 s35, s35, 0
	s_mov_b32 m0, s60
	v_lshl_add_u64 v[232:233], s[34:35], 0, v[136:137]
	ds_read_b128 v[192:195], v163 offset:32768
	ds_read_b128 v[196:199], v163 offset:33792
	ds_read_b128 v[200:203], v163 offset:34816
	ds_read_b128 v[204:207], v163 offset:35840
	ds_read_b128 v[208:211], v163 offset:36864
	ds_read_b128 v[212:215], v163 offset:37888
	ds_read_b128 v[216:219], v163 offset:38912
	ds_read_b128 v[220:223], v163 offset:39936
	global_load_lds_dwordx4 v[232:233], off
	v_lshl_add_u64 v[232:233], s[34:35], 0, v[132:133]
	s_mov_b32 m0, s61
	s_nop 0
	global_load_lds_dwordx4 v[232:233], off
	s_waitcnt vmcnt(8)
	s_waitcnt lgkmcnt(0)
	s_barrier
	v_mfma_f32_16x16x32_bf16 v[42:45], v[154:157], v[192:195], v[42:45]
	v_mfma_f32_16x16x32_bf16 v[42:45], v[164:167], v[196:199], v[42:45]
	v_mfma_f32_16x16x32_bf16 v[54:57], v[164:167], v[204:207], v[54:57]
	v_mfma_f32_16x16x32_bf16 v[54:57], v[154:157], v[200:203], v[54:57]
	v_mfma_f32_16x16x32_bf16 v[66:69], v[154:157], v[208:211], v[66:69]
	v_mfma_f32_16x16x32_bf16 v[66:69], v[164:167], v[212:215], v[66:69]
	v_mfma_f32_16x16x32_bf16 v[62:65], v[164:167], v[220:223], v[62:65]
	v_mfma_f32_16x16x32_bf16 v[62:65], v[154:157], v[216:219], v[62:65]
	v_mfma_f32_16x16x32_bf16 v[46:49], v[168:171], v[216:219], v[46:49]
	v_mfma_f32_16x16x32_bf16 v[46:49], v[172:175], v[220:223], v[46:49]
	v_mfma_f32_16x16x32_bf16 v[50:53], v[172:175], v[212:215], v[50:53]
	v_mfma_f32_16x16x32_bf16 v[50:53], v[168:171], v[208:211], v[50:53]
	v_mfma_f32_16x16x32_bf16 v[38:41], v[168:171], v[200:203], v[38:41]
	v_mfma_f32_16x16x32_bf16 v[38:41], v[172:175], v[204:207], v[38:41]
	v_mfma_f32_16x16x32_bf16 v[26:29], v[172:175], v[196:199], v[26:29]
	v_mfma_f32_16x16x32_bf16 v[26:29], v[168:171], v[192:195], v[26:29]
	v_mfma_f32_16x16x32_bf16 v[14:17], v[176:179], v[192:195], v[14:17]
	v_mfma_f32_16x16x32_bf16 v[14:17], v[180:183], v[196:199], v[14:17]
	v_mfma_f32_16x16x32_bf16 v[22:25], v[180:183], v[204:207], v[22:25]
	v_mfma_f32_16x16x32_bf16 v[22:25], v[176:179], v[200:203], v[22:25]
	v_mfma_f32_16x16x32_bf16 v[30:33], v[176:179], v[208:211], v[30:33]
	v_mfma_f32_16x16x32_bf16 v[30:33], v[180:183], v[212:215], v[30:33]
	v_mfma_f32_16x16x32_bf16 v[34:37], v[180:183], v[220:223], v[34:37]
	v_mfma_f32_16x16x32_bf16 v[34:37], v[176:179], v[216:219], v[34:37]
	v_mfma_f32_16x16x32_bf16 v[18:21], v[184:187], v[216:219], v[18:21]
	v_mfma_f32_16x16x32_bf16 v[18:21], v[188:191], v[220:223], v[18:21]
	v_mfma_f32_16x16x32_bf16 v[10:13], v[188:191], v[212:215], v[10:13]
	v_mfma_f32_16x16x32_bf16 v[10:13], v[184:187], v[208:211], v[10:13]
	v_mfma_f32_16x16x32_bf16 v[6:9], v[184:187], v[200:203], v[6:9]
	v_mfma_f32_16x16x32_bf16 v[6:9], v[188:191], v[204:207], v[6:9]
	v_mfma_f32_16x16x32_bf16 v[2:5], v[188:191], v[196:199], v[2:5]
	v_mfma_f32_16x16x32_bf16 v[2:5], v[184:187], v[192:195], v[2:5]
	s_barrier
	s_add_i32 s34, s50, s54
	v_lshl_add_u64 v[224:225], v[224:225], 0, s[10:11]
	s_mov_b32 m0, s34
	ds_read_b128 v[192:195], v163 offset:49152
	ds_read_b128 v[196:199], v163 offset:50176
	ds_read_b128 v[200:203], v163 offset:51200
	ds_read_b128 v[204:207], v163 offset:52224
	ds_read_b128 v[208:211], v163 offset:53248
	ds_read_b128 v[212:215], v163 offset:54272
	ds_read_b128 v[216:219], v163 offset:55296
	ds_read_b128 v[220:223], v163 offset:56320
	global_load_lds_dwordx4 v[224:225], off
	s_add_i32 m0, s34, 0x2000
	s_add_u32 s30, s30, 0x40080
	v_lshl_add_u64 v[224:225], v[226:227], 0, s[10:11]
	s_addc_u32 s31, s31, 0
	s_add_i32 s34, s51, s54
	global_load_lds_dwordx4 v[224:225], off
	v_lshl_add_u64 v[224:225], s[30:31], 0, v[134:135]
	s_mov_b32 m0, s34
	s_nop 0
	global_load_lds_dwordx4 v[224:225], off
	v_lshl_add_u64 v[224:225], s[30:31], 0, v[130:131]
	s_add_i32 m0, s34, 0x2000
	s_nop 0
	global_load_lds_dwordx4 v[224:225], off
	v_lshl_add_u64 v[224:225], v[228:229], 0, s[10:11]
	s_mov_b32 m0, s65
	s_nop 0
	global_load_lds_dwordx4 v[224:225], off
	v_lshl_add_u64 v[224:225], v[230:231], 0, s[10:11]
	s_mov_b32 m0, s66
	s_nop 0
	global_load_lds_dwordx4 v[224:225], off
	s_waitcnt vmcnt(8)
	s_waitcnt lgkmcnt(0)
	s_barrier
	v_mfma_f32_16x16x32_bf16 v[110:113], v[154:157], v[192:195], v[110:113]
	v_mfma_f32_16x16x32_bf16 v[110:113], v[164:167], v[196:199], v[110:113]
	v_mfma_f32_16x16x32_bf16 v[106:109], v[164:167], v[204:207], v[106:109]
	v_mfma_f32_16x16x32_bf16 v[106:109], v[154:157], v[200:203], v[106:109]
	v_mfma_f32_16x16x32_bf16 v[118:121], v[154:157], v[208:211], v[118:121]
	v_mfma_f32_16x16x32_bf16 v[118:121], v[164:167], v[212:215], v[118:121]
	v_mfma_f32_16x16x32_bf16 v[126:129], v[164:167], v[220:223], v[126:129]
	v_mfma_f32_16x16x32_bf16 v[126:129], v[154:157], v[216:219], v[126:129]
	v_mfma_f32_16x16x32_bf16 v[102:105], v[168:171], v[216:219], v[102:105]
	v_mfma_f32_16x16x32_bf16 v[102:105], v[172:175], v[220:223], v[102:105]
	v_mfma_f32_16x16x32_bf16 v[94:97], v[172:175], v[212:215], v[94:97]
	v_mfma_f32_16x16x32_bf16 v[94:97], v[168:171], v[208:211], v[94:97]
	v_mfma_f32_16x16x32_bf16 v[82:85], v[168:171], v[200:203], v[82:85]
	v_mfma_f32_16x16x32_bf16 v[82:85], v[172:175], v[204:207], v[82:85]
	v_mfma_f32_16x16x32_bf16 v[86:89], v[172:175], v[196:199], v[86:89]
	v_mfma_f32_16x16x32_bf16 v[86:89], v[168:171], v[192:195], v[86:89]
	v_mfma_f32_16x16x32_bf16 v[70:73], v[176:179], v[192:195], v[70:73]
	v_mfma_f32_16x16x32_bf16 v[70:73], v[180:183], v[196:199], v[70:73]
	v_mfma_f32_16x16x32_bf16 v[74:77], v[180:183], v[204:207], v[74:77]
	v_mfma_f32_16x16x32_bf16 v[74:77], v[176:179], v[200:203], v[74:77]
	v_mfma_f32_16x16x32_bf16 v[114:117], v[176:179], v[208:211], v[114:117]
	v_mfma_f32_16x16x32_bf16 v[114:117], v[180:183], v[212:215], v[114:117]
	v_mfma_f32_16x16x32_bf16 v[122:125], v[180:183], v[220:223], v[122:125]
	v_mfma_f32_16x16x32_bf16 v[122:125], v[176:179], v[216:219], v[122:125]
	v_mfma_f32_16x16x32_bf16 v[98:101], v[184:187], v[216:219], v[98:101]
	v_mfma_f32_16x16x32_bf16 v[98:101], v[188:191], v[220:223], v[98:101]
	v_mfma_f32_16x16x32_bf16 v[90:93], v[188:191], v[212:215], v[90:93]
	v_mfma_f32_16x16x32_bf16 v[90:93], v[184:187], v[208:211], v[90:93]
	v_mfma_f32_16x16x32_bf16 v[78:81], v[184:187], v[200:203], v[78:81]
	v_mfma_f32_16x16x32_bf16 v[78:81], v[188:191], v[204:207], v[78:81]
	v_mfma_f32_16x16x32_bf16 v[58:61], v[188:191], v[196:199], v[58:61]
	v_mfma_f32_16x16x32_bf16 v[58:61], v[184:187], v[192:195], v[58:61]
	s_barrier
	s_add_u32 s28, s28, 0x100
	s_addc_u32 s29, s29, 0
	s_add_u32 s17, s17, 0x100
	s_addc_u32 s19, s19, 0
	s_cmp_ge_i32 s75, s62
	s_mov_b32 s30, s75
	s_cbranch_scc0 .LBB0_256

.LBB0_351:
	v_add_u32_e32 v81, s62, v78
	s_waitcnt lgkmcnt(0)
	ds_read_b128 v[82:85], v81
	ds_read_b128 v[86:89], v81 offset:1024
	ds_read_b128 v[90:93], v81 offset:2048
	ds_read_b128 v[94:97], v81 offset:3072
	s_add_i32 s72, s24, 2
	s_add_u32 s22, s20, 0x100
	s_addc_u32 s23, s21, 0
	s_cmp_eq_u32 s61, s24
	s_cselect_b32 s24, s16, s70
	s_cselect_b32 s27, s15, s23
	s_cselect_b32 s26, s14, s22
	s_cselect_b32 s25, s17, s71
	s_mov_b32 m0, s63
	v_lshl_add_u64 v[130:131], s[20:21], 0, v[74:75]
	ds_read_b128 v[98:101], v79
	ds_read_b128 v[102:105], v79 offset:1024
	ds_read_b128 v[106:109], v79 offset:2048
	ds_read_b128 v[110:113], v79 offset:3072
	ds_read_b128 v[114:117], v79 offset:4096
	ds_read_b128 v[118:121], v79 offset:5120
	ds_read_b128 v[122:125], v79 offset:6144
	ds_read_b128 v[126:129], v79 offset:7168
	global_load_lds_dwordx4 v[130:131], off
	v_lshl_add_u64 v[130:131], s[20:21], 0, v[76:77]
	s_mov_b32 m0, s64
	s_nop 0
	global_load_lds_dwordx4 v[130:131], off
	s_waitcnt vmcnt(8)
	s_waitcnt lgkmcnt(0)
	s_barrier
	v_mfma_f32_16x16x32_bf16 v[62:65], v[82:85], v[98:101], v[62:65]
	v_mfma_f32_16x16x32_bf16 v[62:65], v[86:89], v[102:105], v[62:65]
	v_mfma_f32_16x16x32_bf16 v[54:57], v[86:89], v[110:113], v[54:57]
	v_mfma_f32_16x16x32_bf16 v[54:57], v[82:85], v[106:109], v[54:57]
	v_mfma_f32_16x16x32_bf16 v[46:49], v[82:85], v[114:117], v[46:49]
	v_mfma_f32_16x16x32_bf16 v[46:49], v[86:89], v[118:121], v[46:49]
	v_mfma_f32_16x16x32_bf16 v[34:37], v[86:89], v[126:129], v[34:37]
	v_mfma_f32_16x16x32_bf16 v[34:37], v[82:85], v[122:125], v[34:37]
	v_mfma_f32_16x16x32_bf16 v[26:29], v[90:93], v[122:125], v[26:29]
	v_mfma_f32_16x16x32_bf16 v[26:29], v[94:97], v[126:129], v[26:29]
	v_mfma_f32_16x16x32_bf16 v[42:45], v[94:97], v[118:121], v[42:45]
	v_mfma_f32_16x16x32_bf16 v[42:45], v[90:93], v[114:117], v[42:45]
	v_mfma_f32_16x16x32_bf16 v[50:53], v[90:93], v[106:109], v[50:53]
	v_mfma_f32_16x16x32_bf16 v[50:53], v[94:97], v[110:113], v[50:53]
	v_mfma_f32_16x16x32_bf16 v[58:61], v[94:97], v[102:105], v[58:61]
	v_mfma_f32_16x16x32_bf16 v[58:61], v[90:93], v[98:101], v[58:61]
	s_barrier
	s_mov_b32 m0, s65
	v_lshl_add_u64 v[130:131], s[24:25], 0, v[70:71]
	s_add_u32 s20, s24, 0x10000
	ds_read_b128 v[98:101], v79 offset:16384
	ds_read_b128 v[102:105], v79 offset:17408
	ds_read_b128 v[106:109], v79 offset:18432
	ds_read_b128 v[110:113], v79 offset:19456
	ds_read_b128 v[114:117], v79 offset:20480
	ds_read_b128 v[118:121], v79 offset:21504
	ds_read_b128 v[122:125], v79 offset:22528
	ds_read_b128 v[126:129], v79 offset:23552
	global_load_lds_dwordx4 v[130:131], off
	v_lshl_add_u64 v[132:133], s[24:25], 0, v[66:67]
	s_mov_b32 m0, s66
	s_addc_u32 s21, s25, 0
	global_load_lds_dwordx4 v[132:133], off
	v_lshl_add_u64 v[134:135], s[20:21], 0, v[70:71]
	s_mov_b32 m0, s34
	v_lshl_add_u64 v[136:137], s[26:27], 0, v[68:69]
	global_load_lds_dwordx4 v[134:135], off
	v_lshl_add_u64 v[134:135], s[20:21], 0, v[66:67]
	s_mov_b32 m0, s35
	s_nop 0
	global_load_lds_dwordx4 v[134:135], off
	v_lshl_add_u64 v[134:135], s[26:27], 0, v[72:73]
	s_mov_b32 m0, s31
	s_nop 0
	global_load_lds_dwordx4 v[134:135], off
	s_mov_b32 m0, s52
	s_nop 0
	global_load_lds_dwordx4 v[136:137], off
	s_waitcnt vmcnt(8)
	s_waitcnt lgkmcnt(0)
	s_barrier
	v_mfma_f32_16x16x32_bf16 v[38:41], v[82:85], v[98:101], v[38:41]
	v_mfma_f32_16x16x32_bf16 v[38:41], v[86:89], v[102:105], v[38:41]
	v_mfma_f32_16x16x32_bf16 v[22:25], v[86:89], v[110:113], v[22:25]
	v_mfma_f32_16x16x32_bf16 v[22:25], v[82:85], v[106:109], v[22:25]
	v_mfma_f32_16x16x32_bf16 v[14:17], v[82:85], v[114:117], v[14:17]
	v_mfma_f32_16x16x32_bf16 v[14:17], v[86:89], v[118:121], v[14:17]
	v_mfma_f32_16x16x32_bf16 v[6:9], v[86:89], v[126:129], v[6:9]
	v_mfma_f32_16x16x32_bf16 v[6:9], v[82:85], v[122:125], v[6:9]
	v_mfma_f32_16x16x32_bf16 v[2:5], v[90:93], v[122:125], v[2:5]
	v_mfma_f32_16x16x32_bf16 v[2:5], v[94:97], v[126:129], v[2:5]
	v_mfma_f32_16x16x32_bf16 v[10:13], v[94:97], v[118:121], v[10:13]
	v_mfma_f32_16x16x32_bf16 v[10:13], v[90:93], v[114:117], v[10:13]
	v_mfma_f32_16x16x32_bf16 v[18:21], v[90:93], v[106:109], v[18:21]
	v_mfma_f32_16x16x32_bf16 v[18:21], v[94:97], v[110:113], v[18:21]
	v_mfma_f32_16x16x32_bf16 v[30:33], v[94:97], v[102:105], v[30:33]
	v_mfma_f32_16x16x32_bf16 v[30:33], v[90:93], v[98:101], v[30:33]
	s_barrier
	v_add_u32_e32 v81, s67, v78
	ds_read_b128 v[82:85], v81
	ds_read_b128 v[86:89], v81 offset:1024
	ds_read_b128 v[90:93], v81 offset:2048
	ds_read_b128 v[94:97], v81 offset:3072
	s_add_u32 s20, s26, 0x18000
	s_addc_u32 s21, s27, 0
	s_mov_b32 m0, s53
	v_lshl_add_u64 v[138:139], s[20:21], 0, v[72:73]
	ds_read_b128 v[98:101], v79 offset:32768
	ds_read_b128 v[102:105], v79 offset:33792
	ds_read_b128 v[106:109], v79 offset:34816
	ds_read_b128 v[110:113], v79 offset:35840
	ds_read_b128 v[114:117], v79 offset:36864
	ds_read_b128 v[118:121], v79 offset:37888
	ds_read_b128 v[122:125], v79 offset:38912
	ds_read_b128 v[126:129], v79 offset:39936
	global_load_lds_dwordx4 v[138:139], off
	v_lshl_add_u64 v[138:139], s[20:21], 0, v[68:69]
	s_mov_b32 m0, s54
	s_nop 0
	global_load_lds_dwordx4 v[138:139], off
	s_waitcnt vmcnt(8)
	s_waitcnt lgkmcnt(0)
	s_barrier
	v_mfma_f32_16x16x32_bf16 v[62:65], v[82:85], v[98:101], v[62:65]
	v_mfma_f32_16x16x32_bf16 v[62:65], v[86:89], v[102:105], v[62:65]
	v_mfma_f32_16x16x32_bf16 v[54:57], v[86:89], v[110:113], v[54:57]
	v_mfma_f32_16x16x32_bf16 v[54:57], v[82:85], v[106:109], v[54:57]
	v_mfma_f32_16x16x32_bf16 v[46:49], v[82:85], v[114:117], v[46:49]
	v_mfma_f32_16x16x32_bf16 v[46:49], v[86:89], v[118:121], v[46:49]
	v_mfma_f32_16x16x32_bf16 v[34:37], v[86:89], v[126:129], v[34:37]
	v_mfma_f32_16x16x32_bf16 v[34:37], v[82:85], v[122:125], v[34:37]
	v_mfma_f32_16x16x32_bf16 v[26:29], v[90:93], v[122:125], v[26:29]
	v_mfma_f32_16x16x32_bf16 v[26:29], v[94:97], v[126:129], v[26:29]
	v_mfma_f32_16x16x32_bf16 v[42:45], v[94:97], v[118:121], v[42:45]
	v_mfma_f32_16x16x32_bf16 v[42:45], v[90:93], v[114:117], v[42:45]
	v_mfma_f32_16x16x32_bf16 v[50:53], v[90:93], v[106:109], v[50:53]
	v_mfma_f32_16x16x32_bf16 v[50:53], v[94:97], v[110:113], v[50:53]
	v_mfma_f32_16x16x32_bf16 v[58:61], v[94:97], v[102:105], v[58:61]
	v_mfma_f32_16x16x32_bf16 v[58:61], v[90:93], v[98:101], v[58:61]
	s_barrier
	s_mov_b32 m0, s68
	v_lshl_add_u64 v[130:131], v[130:131], 0, s[6:7]
	s_add_u32 s20, s24, 0x10080
	ds_read_b128 v[98:101], v79 offset:49152
	ds_read_b128 v[102:105], v79 offset:50176
	ds_read_b128 v[106:109], v79 offset:51200
	ds_read_b128 v[110:113], v79 offset:52224
	ds_read_b128 v[114:117], v79 offset:53248
	ds_read_b128 v[118:121], v79 offset:54272
	ds_read_b128 v[122:125], v79 offset:55296
	ds_read_b128 v[126:129], v79 offset:56320
	global_load_lds_dwordx4 v[130:131], off
	v_lshl_add_u64 v[130:131], v[132:133], 0, s[6:7]
	s_mov_b32 m0, s69
	s_addc_u32 s21, s25, 0
	global_load_lds_dwordx4 v[130:131], off
	v_lshl_add_u64 v[130:131], s[20:21], 0, v[70:71]
	s_mov_b32 m0, s59
	s_nop 0
	global_load_lds_dwordx4 v[130:131], off
	v_lshl_add_u64 v[130:131], s[20:21], 0, v[66:67]
	s_mov_b32 m0, s60
	s_nop 0
	global_load_lds_dwordx4 v[130:131], off
	v_lshl_add_u64 v[130:131], v[134:135], 0, s[6:7]
	s_mov_b32 m0, s57
	s_nop 0
	global_load_lds_dwordx4 v[130:131], off
	v_lshl_add_u64 v[130:131], v[136:137], 0, s[6:7]
	s_mov_b32 m0, s58
	s_nop 0
	global_load_lds_dwordx4 v[130:131], off
	s_waitcnt vmcnt(8)
	s_waitcnt lgkmcnt(0)
	s_barrier
	v_mfma_f32_16x16x32_bf16 v[38:41], v[82:85], v[98:101], v[38:41]
	v_mfma_f32_16x16x32_bf16 v[38:41], v[86:89], v[102:105], v[38:41]
	v_mfma_f32_16x16x32_bf16 v[22:25], v[86:89], v[110:113], v[22:25]
	v_mfma_f32_16x16x32_bf16 v[22:25], v[82:85], v[106:109], v[22:25]
	v_mfma_f32_16x16x32_bf16 v[14:17], v[82:85], v[114:117], v[14:17]
	v_mfma_f32_16x16x32_bf16 v[14:17], v[86:89], v[118:121], v[14:17]
	v_mfma_f32_16x16x32_bf16 v[6:9], v[86:89], v[126:129], v[6:9]
	v_mfma_f32_16x16x32_bf16 v[6:9], v[82:85], v[122:125], v[6:9]
	v_mfma_f32_16x16x32_bf16 v[2:5], v[90:93], v[122:125], v[2:5]
	v_mfma_f32_16x16x32_bf16 v[2:5], v[94:97], v[126:129], v[2:5]
	v_mfma_f32_16x16x32_bf16 v[10:13], v[94:97], v[118:121], v[10:13]
	v_mfma_f32_16x16x32_bf16 v[10:13], v[90:93], v[114:117], v[10:13]
	v_mfma_f32_16x16x32_bf16 v[18:21], v[90:93], v[106:109], v[18:21]
	v_mfma_f32_16x16x32_bf16 v[18:21], v[94:97], v[110:113], v[18:21]
	v_mfma_f32_16x16x32_bf16 v[30:33], v[94:97], v[102:105], v[30:33]
	v_mfma_f32_16x16x32_bf16 v[30:33], v[90:93], v[98:101], v[30:33]
	s_barrier
	s_add_u32 s70, s70, 0x100
	s_addc_u32 s71, s71, 0
	s_cmp_ge_i32 s72, s56
	s_mov_b64 s[20:21], s[22:23]
	s_mov_b32 s24, s72
	s_cbranch_scc0 .LBB0_351

.LBB0_468:
	v_add_u32_e32 v144, s62, v1
	ds_read_b128 v[150:153], v144
	ds_read_b128 v[154:157], v144 offset:1024
	ds_read_b128 v[158:161], v144 offset:2048
	ds_read_b128 v[162:165], v144 offset:3072
	v_add_u32_e32 v144, s63, v1
	ds_read_b128 v[166:169], v144
	ds_read_b128 v[170:173], v144 offset:1024
	ds_read_b128 v[174:177], v144 offset:2048
	ds_read_b128 v[178:181], v144 offset:3072
	s_add_i32 s77, s26, 2
	s_add_u32 s24, s22, 0x100
	s_addc_u32 s25, s23, 0
	s_cmp_eq_u32 s61, s26
	s_cselect_b32 s26, s16, s75
	s_cselect_b32 s29, s15, s25
	s_cselect_b32 s28, s14, s24
	s_cselect_b32 s27, s17, s76
	s_mov_b32 m0, s64
	v_lshl_add_u64 v[144:145], s[22:23], 0, v[140:141]
	ds_read_b128 v[182:185], v149
	ds_read_b128 v[186:189], v149 offset:1024
	ds_read_b128 v[190:193], v149 offset:2048
	ds_read_b128 v[194:197], v149 offset:3072
	ds_read_b128 v[198:201], v149 offset:4096
	ds_read_b128 v[202:205], v149 offset:5120
	ds_read_b128 v[206:209], v149 offset:6144
	ds_read_b128 v[210:213], v149 offset:7168
	global_load_lds_dwordx4 v[144:145], off
	v_lshl_add_u64 v[144:145], s[22:23], 0, v[142:143]
	s_mov_b32 m0, s65
	s_nop 0
	global_load_lds_dwordx4 v[144:145], off
	s_waitcnt vmcnt(8)
	s_waitcnt lgkmcnt(0)
	s_barrier
	v_mfma_f32_16x16x32_bf16 v[126:129], v[150:153], v[182:185], v[126:129]
	v_mfma_f32_16x16x32_bf16 v[126:129], v[154:157], v[186:189], v[126:129]
	v_mfma_f32_16x16x32_bf16 v[110:113], v[154:157], v[194:197], v[110:113]
	v_mfma_f32_16x16x32_bf16 v[110:113], v[150:153], v[190:193], v[110:113]
	v_mfma_f32_16x16x32_bf16 v[94:97], v[150:153], v[198:201], v[94:97]
	v_mfma_f32_16x16x32_bf16 v[94:97], v[154:157], v[202:205], v[94:97]
	v_mfma_f32_16x16x32_bf16 v[78:81], v[154:157], v[210:213], v[78:81]
	v_mfma_f32_16x16x32_bf16 v[78:81], v[150:153], v[206:209], v[78:81]
	v_mfma_f32_16x16x32_bf16 v[74:77], v[158:161], v[206:209], v[74:77]
	v_mfma_f32_16x16x32_bf16 v[74:77], v[162:165], v[210:213], v[74:77]
	v_mfma_f32_16x16x32_bf16 v[90:93], v[162:165], v[202:205], v[90:93]
	v_mfma_f32_16x16x32_bf16 v[90:93], v[158:161], v[198:201], v[90:93]
	v_mfma_f32_16x16x32_bf16 v[106:109], v[158:161], v[190:193], v[106:109]
	v_mfma_f32_16x16x32_bf16 v[106:109], v[162:165], v[194:197], v[106:109]
	v_mfma_f32_16x16x32_bf16 v[122:125], v[162:165], v[186:189], v[122:125]
	v_mfma_f32_16x16x32_bf16 v[122:125], v[158:161], v[182:185], v[122:125]
	v_mfma_f32_16x16x32_bf16 v[118:121], v[166:169], v[182:185], v[118:121]
	v_mfma_f32_16x16x32_bf16 v[118:121], v[170:173], v[186:189], v[118:121]
	v_mfma_f32_16x16x32_bf16 v[102:105], v[170:173], v[194:197], v[102:105]
	v_mfma_f32_16x16x32_bf16 v[102:105], v[166:169], v[190:193], v[102:105]
	v_mfma_f32_16x16x32_bf16 v[86:89], v[166:169], v[198:201], v[86:89]
	v_mfma_f32_16x16x32_bf16 v[86:89], v[170:173], v[202:205], v[86:89]
	v_mfma_f32_16x16x32_bf16 v[70:73], v[170:173], v[210:213], v[70:73]
	v_mfma_f32_16x16x32_bf16 v[70:73], v[166:169], v[206:209], v[70:73]
	v_mfma_f32_16x16x32_bf16 v[66:69], v[174:177], v[206:209], v[66:69]
	v_mfma_f32_16x16x32_bf16 v[66:69], v[178:181], v[210:213], v[66:69]
	v_mfma_f32_16x16x32_bf16 v[82:85], v[178:181], v[202:205], v[82:85]
	v_mfma_f32_16x16x32_bf16 v[82:85], v[174:177], v[198:201], v[82:85]
	v_mfma_f32_16x16x32_bf16 v[98:101], v[174:177], v[190:193], v[98:101]
	v_mfma_f32_16x16x32_bf16 v[98:101], v[178:181], v[194:197], v[98:101]
	v_mfma_f32_16x16x32_bf16 v[114:117], v[178:181], v[186:189], v[114:117]
	v_mfma_f32_16x16x32_bf16 v[114:117], v[174:177], v[182:185], v[114:117]
	s_barrier
	s_mov_b32 m0, s66
	v_lshl_add_u64 v[144:145], s[26:27], 0, v[134:135]
	s_add_u32 s22, s26, 0x18000
	ds_read_b128 v[182:185], v149 offset:16384
	ds_read_b128 v[186:189], v149 offset:17408
	ds_read_b128 v[190:193], v149 offset:18432
	ds_read_b128 v[194:197], v149 offset:19456
	ds_read_b128 v[198:201], v149 offset:20480
	ds_read_b128 v[202:205], v149 offset:21504
	ds_read_b128 v[206:209], v149 offset:22528
	ds_read_b128 v[210:213], v149 offset:23552
	global_load_lds_dwordx4 v[144:145], off
	v_lshl_add_u64 v[214:215], s[26:27], 0, v[130:131]
	s_mov_b32 m0, s67
	s_addc_u32 s23, s27, 0
	global_load_lds_dwordx4 v[214:215], off
	v_lshl_add_u64 v[216:217], s[22:23], 0, v[134:135]
	s_mov_b32 m0, s68
	v_lshl_add_u64 v[218:219], s[28:29], 0, v[132:133]
	global_load_lds_dwordx4 v[216:217], off
	v_lshl_add_u64 v[216:217], s[22:23], 0, v[130:131]
	s_mov_b32 m0, s69
	s_nop 0
	global_load_lds_dwordx4 v[216:217], off
	v_lshl_add_u64 v[216:217], s[28:29], 0, v[136:137]
	s_mov_b32 m0, s34
	s_nop 0
	global_load_lds_dwordx4 v[216:217], off
	s_mov_b32 m0, s35
	s_nop 0
	global_load_lds_dwordx4 v[218:219], off
	s_waitcnt vmcnt(8)
	s_waitcnt lgkmcnt(0)
	s_barrier
	v_mfma_f32_16x16x32_bf16 v[62:65], v[150:153], v[182:185], v[62:65]
	v_mfma_f32_16x16x32_bf16 v[62:65], v[154:157], v[186:189], v[62:65]
	v_mfma_f32_16x16x32_bf16 v[46:49], v[154:157], v[194:197], v[46:49]
	v_mfma_f32_16x16x32_bf16 v[46:49], v[150:153], v[190:193], v[46:49]
	v_mfma_f32_16x16x32_bf16 v[30:33], v[150:153], v[198:201], v[30:33]
	v_mfma_f32_16x16x32_bf16 v[30:33], v[154:157], v[202:205], v[30:33]
	v_mfma_f32_16x16x32_bf16 v[14:17], v[154:157], v[210:213], v[14:17]
	v_mfma_f32_16x16x32_bf16 v[14:17], v[150:153], v[206:209], v[14:17]
	v_mfma_f32_16x16x32_bf16 v[10:13], v[158:161], v[206:209], v[10:13]
	v_mfma_f32_16x16x32_bf16 v[10:13], v[162:165], v[210:213], v[10:13]
	v_mfma_f32_16x16x32_bf16 v[26:29], v[162:165], v[202:205], v[26:29]
	v_mfma_f32_16x16x32_bf16 v[26:29], v[158:161], v[198:201], v[26:29]
	v_mfma_f32_16x16x32_bf16 v[42:45], v[158:161], v[190:193], v[42:45]
	v_mfma_f32_16x16x32_bf16 v[42:45], v[162:165], v[194:197], v[42:45]
	v_mfma_f32_16x16x32_bf16 v[58:61], v[162:165], v[186:189], v[58:61]
	v_mfma_f32_16x16x32_bf16 v[58:61], v[158:161], v[182:185], v[58:61]
	v_mfma_f32_16x16x32_bf16 v[54:57], v[166:169], v[182:185], v[54:57]
	v_mfma_f32_16x16x32_bf16 v[54:57], v[170:173], v[186:189], v[54:57]
	v_mfma_f32_16x16x32_bf16 v[38:41], v[170:173], v[194:197], v[38:41]
	v_mfma_f32_16x16x32_bf16 v[38:41], v[166:169], v[190:193], v[38:41]
	v_mfma_f32_16x16x32_bf16 v[22:25], v[166:169], v[198:201], v[22:25]
	v_mfma_f32_16x16x32_bf16 v[22:25], v[170:173], v[202:205], v[22:25]
	v_mfma_f32_16x16x32_bf16 v[6:9], v[170:173], v[210:213], v[6:9]
	v_mfma_f32_16x16x32_bf16 v[6:9], v[166:169], v[206:209], v[6:9]
	v_mfma_f32_16x16x32_bf16 v[2:5], v[174:177], v[206:209], v[2:5]
	v_mfma_f32_16x16x32_bf16 v[2:5], v[178:181], v[210:213], v[2:5]
	v_mfma_f32_16x16x32_bf16 v[18:21], v[178:181], v[202:205], v[18:21]
	v_mfma_f32_16x16x32_bf16 v[18:21], v[174:177], v[198:201], v[18:21]
	v_mfma_f32_16x16x32_bf16 v[34:37], v[174:177], v[190:193], v[34:37]
	v_mfma_f32_16x16x32_bf16 v[34:37], v[178:181], v[194:197], v[34:37]
	v_mfma_f32_16x16x32_bf16 v[50:53], v[178:181], v[186:189], v[50:53]
	v_mfma_f32_16x16x32_bf16 v[50:53], v[174:177], v[182:185], v[50:53]
	s_barrier
	v_add_u32_e32 v162, s70, v1
	v_add_u32_e32 v178, s71, v1
	ds_read_b128 v[150:153], v162
	ds_read_b128 v[154:157], v162 offset:1024
	ds_read_b128 v[158:161], v162 offset:2048
	ds_read_b128 v[162:165], v162 offset:3072
	ds_read_b128 v[166:169], v178
	ds_read_b128 v[170:173], v178 offset:1024
	ds_read_b128 v[174:177], v178 offset:2048
	ds_read_b128 v[178:181], v178 offset:3072
	s_add_u32 s22, s28, 0x18000
	s_addc_u32 s23, s29, 0
	s_mov_b32 m0, s52
	v_lshl_add_u64 v[220:221], s[22:23], 0, v[136:137]
	ds_read_b128 v[182:185], v149 offset:32768
	ds_read_b128 v[186:189], v149 offset:33792
	ds_read_b128 v[190:193], v149 offset:34816
	ds_read_b128 v[194:197], v149 offset:35840
	ds_read_b128 v[198:201], v149 offset:36864
	ds_read_b128 v[202:205], v149 offset:37888
	ds_read_b128 v[206:209], v149 offset:38912
	ds_read_b128 v[210:213], v149 offset:39936
	global_load_lds_dwordx4 v[220:221], off
	v_lshl_add_u64 v[220:221], s[22:23], 0, v[132:133]
	s_mov_b32 m0, s53
	s_nop 0
	global_load_lds_dwordx4 v[220:221], off
	s_waitcnt vmcnt(8)
	s_waitcnt lgkmcnt(0)
	s_barrier
	v_mfma_f32_16x16x32_bf16 v[126:129], v[150:153], v[182:185], v[126:129]
	v_mfma_f32_16x16x32_bf16 v[126:129], v[154:157], v[186:189], v[126:129]
	v_mfma_f32_16x16x32_bf16 v[110:113], v[154:157], v[194:197], v[110:113]
	v_mfma_f32_16x16x32_bf16 v[110:113], v[150:153], v[190:193], v[110:113]
	v_mfma_f32_16x16x32_bf16 v[94:97], v[150:153], v[198:201], v[94:97]
	v_mfma_f32_16x16x32_bf16 v[94:97], v[154:157], v[202:205], v[94:97]
	v_mfma_f32_16x16x32_bf16 v[78:81], v[154:157], v[210:213], v[78:81]
	v_mfma_f32_16x16x32_bf16 v[78:81], v[150:153], v[206:209], v[78:81]
	v_mfma_f32_16x16x32_bf16 v[74:77], v[158:161], v[206:209], v[74:77]
	v_mfma_f32_16x16x32_bf16 v[74:77], v[162:165], v[210:213], v[74:77]
	v_mfma_f32_16x16x32_bf16 v[90:93], v[162:165], v[202:205], v[90:93]
	v_mfma_f32_16x16x32_bf16 v[90:93], v[158:161], v[198:201], v[90:93]
	v_mfma_f32_16x16x32_bf16 v[106:109], v[158:161], v[190:193], v[106:109]
	v_mfma_f32_16x16x32_bf16 v[106:109], v[162:165], v[194:197], v[106:109]
	v_mfma_f32_16x16x32_bf16 v[122:125], v[162:165], v[186:189], v[122:125]
	v_mfma_f32_16x16x32_bf16 v[122:125], v[158:161], v[182:185], v[122:125]
	v_mfma_f32_16x16x32_bf16 v[118:121], v[166:169], v[182:185], v[118:121]
	v_mfma_f32_16x16x32_bf16 v[118:121], v[170:173], v[186:189], v[118:121]
	v_mfma_f32_16x16x32_bf16 v[102:105], v[170:173], v[194:197], v[102:105]
	v_mfma_f32_16x16x32_bf16 v[102:105], v[166:169], v[190:193], v[102:105]
	v_mfma_f32_16x16x32_bf16 v[86:89], v[166:169], v[198:201], v[86:89]
	v_mfma_f32_16x16x32_bf16 v[86:89], v[170:173], v[202:205], v[86:89]
	v_mfma_f32_16x16x32_bf16 v[70:73], v[170:173], v[210:213], v[70:73]
	v_mfma_f32_16x16x32_bf16 v[70:73], v[166:169], v[206:209], v[70:73]
	v_mfma_f32_16x16x32_bf16 v[66:69], v[174:177], v[206:209], v[66:69]
	v_mfma_f32_16x16x32_bf16 v[66:69], v[178:181], v[210:213], v[66:69]
	v_mfma_f32_16x16x32_bf16 v[82:85], v[178:181], v[202:205], v[82:85]
	v_mfma_f32_16x16x32_bf16 v[82:85], v[174:177], v[198:201], v[82:85]
	v_mfma_f32_16x16x32_bf16 v[98:101], v[174:177], v[190:193], v[98:101]
	v_mfma_f32_16x16x32_bf16 v[98:101], v[178:181], v[194:197], v[98:101]
	v_mfma_f32_16x16x32_bf16 v[114:117], v[178:181], v[186:189], v[114:117]
	v_mfma_f32_16x16x32_bf16 v[114:117], v[174:177], v[182:185], v[114:117]
	s_barrier
	s_mov_b32 m0, s72
	v_lshl_add_u64 v[144:145], v[144:145], 0, s[4:5]
	ds_read_b128 v[182:185], v149 offset:49152
	ds_read_b128 v[186:189], v149 offset:50176
	ds_read_b128 v[190:193], v149 offset:51200
	ds_read_b128 v[194:197], v149 offset:52224
	ds_read_b128 v[198:201], v149 offset:53248
	ds_read_b128 v[202:205], v149 offset:54272
	ds_read_b128 v[206:209], v149 offset:55296
	ds_read_b128 v[210:213], v149 offset:56320
	global_load_lds_dwordx4 v[144:145], off
	s_add_i32 m0, s72, 0x2000
	s_add_u32 s22, s26, 0x18080
	v_lshl_add_u64 v[144:145], v[214:215], 0, s[4:5]
	s_addc_u32 s23, s27, 0
	s_add_i32 s26, s71, s30
	global_load_lds_dwordx4 v[144:145], off
	v_lshl_add_u64 v[144:145], s[22:23], 0, v[134:135]
	s_mov_b32 m0, s26
	s_nop 0
	global_load_lds_dwordx4 v[144:145], off
	v_lshl_add_u64 v[144:145], s[22:23], 0, v[130:131]
	s_add_i32 m0, s26, 0x2000
	s_nop 0
	global_load_lds_dwordx4 v[144:145], off
	v_lshl_add_u64 v[144:145], v[216:217], 0, s[4:5]
	s_mov_b32 m0, s59
	s_nop 0
	global_load_lds_dwordx4 v[144:145], off
	v_lshl_add_u64 v[144:145], v[218:219], 0, s[4:5]
	s_mov_b32 m0, s60
	s_nop 0
	global_load_lds_dwordx4 v[144:145], off
	s_waitcnt vmcnt(8)
	s_waitcnt lgkmcnt(0)
	s_barrier
	v_mfma_f32_16x16x32_bf16 v[62:65], v[150:153], v[182:185], v[62:65]
	v_mfma_f32_16x16x32_bf16 v[62:65], v[154:157], v[186:189], v[62:65]
	v_mfma_f32_16x16x32_bf16 v[46:49], v[154:157], v[194:197], v[46:49]
	v_mfma_f32_16x16x32_bf16 v[46:49], v[150:153], v[190:193], v[46:49]
	v_mfma_f32_16x16x32_bf16 v[30:33], v[150:153], v[198:201], v[30:33]
	v_mfma_f32_16x16x32_bf16 v[30:33], v[154:157], v[202:205], v[30:33]
	v_mfma_f32_16x16x32_bf16 v[14:17], v[154:157], v[210:213], v[14:17]
	v_mfma_f32_16x16x32_bf16 v[14:17], v[150:153], v[206:209], v[14:17]
	v_mfma_f32_16x16x32_bf16 v[10:13], v[158:161], v[206:209], v[10:13]
	v_mfma_f32_16x16x32_bf16 v[10:13], v[162:165], v[210:213], v[10:13]
	v_mfma_f32_16x16x32_bf16 v[26:29], v[162:165], v[202:205], v[26:29]
	v_mfma_f32_16x16x32_bf16 v[26:29], v[158:161], v[198:201], v[26:29]
	v_mfma_f32_16x16x32_bf16 v[42:45], v[158:161], v[190:193], v[42:45]
	v_mfma_f32_16x16x32_bf16 v[42:45], v[162:165], v[194:197], v[42:45]
	v_mfma_f32_16x16x32_bf16 v[58:61], v[162:165], v[186:189], v[58:61]
	v_mfma_f32_16x16x32_bf16 v[58:61], v[158:161], v[182:185], v[58:61]
	v_mfma_f32_16x16x32_bf16 v[54:57], v[166:169], v[182:185], v[54:57]
	v_mfma_f32_16x16x32_bf16 v[54:57], v[170:173], v[186:189], v[54:57]
	v_mfma_f32_16x16x32_bf16 v[38:41], v[170:173], v[194:197], v[38:41]
	v_mfma_f32_16x16x32_bf16 v[38:41], v[166:169], v[190:193], v[38:41]
	v_mfma_f32_16x16x32_bf16 v[22:25], v[166:169], v[198:201], v[22:25]
	v_mfma_f32_16x16x32_bf16 v[22:25], v[170:173], v[202:205], v[22:25]
	v_mfma_f32_16x16x32_bf16 v[6:9], v[170:173], v[210:213], v[6:9]
	v_mfma_f32_16x16x32_bf16 v[6:9], v[166:169], v[206:209], v[6:9]
	v_mfma_f32_16x16x32_bf16 v[2:5], v[174:177], v[206:209], v[2:5]
	v_mfma_f32_16x16x32_bf16 v[2:5], v[178:181], v[210:213], v[2:5]
	v_mfma_f32_16x16x32_bf16 v[18:21], v[178:181], v[202:205], v[18:21]
	v_mfma_f32_16x16x32_bf16 v[18:21], v[174:177], v[198:201], v[18:21]
	v_mfma_f32_16x16x32_bf16 v[34:37], v[174:177], v[190:193], v[34:37]
	v_mfma_f32_16x16x32_bf16 v[34:37], v[178:181], v[194:197], v[34:37]
	v_mfma_f32_16x16x32_bf16 v[50:53], v[178:181], v[186:189], v[50:53]
	v_mfma_f32_16x16x32_bf16 v[50:53], v[174:177], v[182:185], v[50:53]
	s_barrier
	s_add_u32 s75, s75, 0x100
	s_addc_u32 s76, s76, 0
	s_cmp_ge_i32 s77, s57
	s_mov_b64 s[22:23], s[24:25]
	s_mov_b32 s26, s77
	s_cbranch_scc0 .LBB0_468

.LBB0_599:
	v_add_u32_e32 v142, s74, v199
	v_add_u32_e32 v162, s75, v199
	ds_read_b128 v[130:133], v142
	ds_read_b128 v[134:137], v142 offset:1024
	ds_read_b128 v[138:141], v142 offset:2048
	ds_read_b128 v[142:145], v142 offset:3072
	ds_read_b128 v[146:149], v162
	ds_read_b128 v[150:153], v162 offset:1024
	ds_read_b128 v[174:177], v162 offset:2048
	ds_read_b128 v[178:181], v162 offset:3072
	s_add_i32 s31, s52, 2
	s_add_u32 s50, s34, 0x3ff000
	s_addc_u32 s51, s35, 0
	s_cmp_eq_u32 s71, s52
	s_cselect_b32 s56, s26, s50
	s_cselect_b32 s57, s27, s51
	s_cselect_b32 s54, s28, s23
	s_cselect_b32 s55, s29, s25
	s_add_u32 s52, s56, 0x400000
	s_addc_u32 s53, s57, 0
	v_lshl_add_u64 v[218:219], s[34:35], 0, v[164:165]
	s_add_i32 m0, s59, 0xc000
	ds_read_b128 v[182:185], v200
	ds_read_b128 v[186:189], v200 offset:1024
	ds_read_b128 v[190:193], v200 offset:2048
	ds_read_b128 v[194:197], v200 offset:3072
	ds_read_b128 v[202:205], v200 offset:4096
	ds_read_b128 v[206:209], v200 offset:5120
	ds_read_b128 v[210:213], v200 offset:6144
	ds_read_b128 v[214:217], v200 offset:7168
	global_load_lds_dwordx4 v[218:219], off
	v_lshl_add_u64 v[218:219], s[34:35], 0, v[166:167]
	s_add_i32 m0, s59, 0xe000
	s_nop 0
	global_load_lds_dwordx4 v[218:219], off
	s_waitcnt vmcnt(8)
	s_waitcnt lgkmcnt(0)
	s_barrier
	v_mfma_f32_16x16x32_bf16 v[118:121], v[130:133], v[182:185], v[118:121]
	v_mfma_f32_16x16x32_bf16 v[118:121], v[134:137], v[186:189], v[118:121]
	v_mfma_f32_16x16x32_bf16 v[110:113], v[134:137], v[194:197], v[110:113]
	v_mfma_f32_16x16x32_bf16 v[110:113], v[130:133], v[190:193], v[110:113]
	v_mfma_f32_16x16x32_bf16 v[94:97], v[130:133], v[202:205], v[94:97]
	v_mfma_f32_16x16x32_bf16 v[94:97], v[134:137], v[206:209], v[94:97]
	v_mfma_f32_16x16x32_bf16 v[78:81], v[134:137], v[214:217], v[78:81]
	v_mfma_f32_16x16x32_bf16 v[78:81], v[130:133], v[210:213], v[78:81]
	v_mfma_f32_16x16x32_bf16 v[74:77], v[138:141], v[210:213], v[74:77]
	v_mfma_f32_16x16x32_bf16 v[74:77], v[142:145], v[214:217], v[74:77]
	v_mfma_f32_16x16x32_bf16 v[90:93], v[142:145], v[206:209], v[90:93]
	v_mfma_f32_16x16x32_bf16 v[90:93], v[138:141], v[202:205], v[90:93]
	v_mfma_f32_16x16x32_bf16 v[106:109], v[138:141], v[190:193], v[106:109]
	v_mfma_f32_16x16x32_bf16 v[106:109], v[142:145], v[194:197], v[106:109]
	v_mfma_f32_16x16x32_bf16 v[122:125], v[142:145], v[186:189], v[122:125]
	v_mfma_f32_16x16x32_bf16 v[122:125], v[138:141], v[182:185], v[122:125]
	v_mfma_f32_16x16x32_bf16 v[126:129], v[146:149], v[182:185], v[126:129]
	v_mfma_f32_16x16x32_bf16 v[126:129], v[150:153], v[186:189], v[126:129]
	v_mfma_f32_16x16x32_bf16 v[102:105], v[150:153], v[194:197], v[102:105]
	v_mfma_f32_16x16x32_bf16 v[102:105], v[146:149], v[190:193], v[102:105]
	v_mfma_f32_16x16x32_bf16 v[86:89], v[146:149], v[202:205], v[86:89]
	v_mfma_f32_16x16x32_bf16 v[86:89], v[150:153], v[206:209], v[86:89]
	v_mfma_f32_16x16x32_bf16 v[70:73], v[150:153], v[214:217], v[70:73]
	v_mfma_f32_16x16x32_bf16 v[70:73], v[146:149], v[210:213], v[70:73]
	v_mfma_f32_16x16x32_bf16 v[66:69], v[174:177], v[210:213], v[66:69]
	v_mfma_f32_16x16x32_bf16 v[66:69], v[178:181], v[214:217], v[66:69]
	v_mfma_f32_16x16x32_bf16 v[82:85], v[178:181], v[206:209], v[82:85]
	v_mfma_f32_16x16x32_bf16 v[82:85], v[174:177], v[202:205], v[82:85]
	v_mfma_f32_16x16x32_bf16 v[98:101], v[174:177], v[190:193], v[98:101]
	v_mfma_f32_16x16x32_bf16 v[98:101], v[178:181], v[194:197], v[98:101]
	v_mfma_f32_16x16x32_bf16 v[114:117], v[178:181], v[186:189], v[114:117]
	v_mfma_f32_16x16x32_bf16 v[114:117], v[174:177], v[182:185], v[114:117]
	s_barrier
	s_add_i32 s50, s74, s41
	v_lshl_add_u64 v[218:219], s[54:55], 0, v[156:157]
	s_mov_b32 m0, s50
	ds_read_b128 v[182:185], v200 offset:16384
	ds_read_b128 v[186:189], v200 offset:17408
	ds_read_b128 v[190:193], v200 offset:18432
	ds_read_b128 v[194:197], v200 offset:19456
	ds_read_b128 v[202:205], v200 offset:20480
	ds_read_b128 v[206:209], v200 offset:21504
	ds_read_b128 v[210:213], v200 offset:22528
	ds_read_b128 v[214:217], v200 offset:23552
	global_load_lds_dwordx4 v[218:219], off
	s_add_i32 m0, s50, 0x2000
	s_add_u32 s50, s54, 0x20000
	v_lshl_add_u64 v[220:221], s[54:55], 0, v[160:161]
	s_addc_u32 s51, s55, 0
	s_add_i32 s78, s75, s41
	global_load_lds_dwordx4 v[220:221], off
	v_lshl_add_u64 v[222:223], s[50:51], 0, v[156:157]
	s_mov_b32 m0, s78
	s_nop 0
	global_load_lds_dwordx4 v[222:223], off
	v_lshl_add_u64 v[222:223], s[50:51], 0, v[160:161]
	s_add_i32 m0, s78, 0x2000
	s_nop 0
	global_load_lds_dwordx4 v[222:223], off
	v_lshl_add_u64 v[222:223], s[56:57], 0, v[154:155]
	s_mov_b32 m0, s59
	s_nop 0
	global_load_lds_dwordx4 v[222:223], off
	v_lshl_add_u64 v[222:223], s[56:57], 0, v[158:159]
	s_mov_b32 m0, s60
	s_nop 0
	global_load_lds_dwordx4 v[222:223], off
	s_waitcnt vmcnt(8)
	s_waitcnt lgkmcnt(0)
	s_barrier
	v_mfma_f32_16x16x32_bf16 v[62:65], v[130:133], v[182:185], v[62:65]
	v_mfma_f32_16x16x32_bf16 v[62:65], v[134:137], v[186:189], v[62:65]
	v_mfma_f32_16x16x32_bf16 v[46:49], v[134:137], v[194:197], v[46:49]
	v_mfma_f32_16x16x32_bf16 v[46:49], v[130:133], v[190:193], v[46:49]
	v_mfma_f32_16x16x32_bf16 v[30:33], v[130:133], v[202:205], v[30:33]
	v_mfma_f32_16x16x32_bf16 v[30:33], v[134:137], v[206:209], v[30:33]
	v_mfma_f32_16x16x32_bf16 v[14:17], v[134:137], v[214:217], v[14:17]
	v_mfma_f32_16x16x32_bf16 v[14:17], v[130:133], v[210:213], v[14:17]
	v_mfma_f32_16x16x32_bf16 v[10:13], v[138:141], v[210:213], v[10:13]
	v_mfma_f32_16x16x32_bf16 v[10:13], v[142:145], v[214:217], v[10:13]
	v_mfma_f32_16x16x32_bf16 v[26:29], v[142:145], v[206:209], v[26:29]
	v_mfma_f32_16x16x32_bf16 v[26:29], v[138:141], v[202:205], v[26:29]
	v_mfma_f32_16x16x32_bf16 v[42:45], v[138:141], v[190:193], v[42:45]
	v_mfma_f32_16x16x32_bf16 v[42:45], v[142:145], v[194:197], v[42:45]
	v_mfma_f32_16x16x32_bf16 v[58:61], v[142:145], v[186:189], v[58:61]
	v_mfma_f32_16x16x32_bf16 v[58:61], v[138:141], v[182:185], v[58:61]
	v_mfma_f32_16x16x32_bf16 v[54:57], v[146:149], v[182:185], v[54:57]
	v_mfma_f32_16x16x32_bf16 v[54:57], v[150:153], v[186:189], v[54:57]
	v_mfma_f32_16x16x32_bf16 v[38:41], v[150:153], v[194:197], v[38:41]
	v_mfma_f32_16x16x32_bf16 v[38:41], v[146:149], v[190:193], v[38:41]
	v_mfma_f32_16x16x32_bf16 v[22:25], v[146:149], v[202:205], v[22:25]
	v_mfma_f32_16x16x32_bf16 v[22:25], v[150:153], v[206:209], v[22:25]
	v_mfma_f32_16x16x32_bf16 v[6:9], v[150:153], v[214:217], v[6:9]
	v_mfma_f32_16x16x32_bf16 v[6:9], v[146:149], v[210:213], v[6:9]
	v_mfma_f32_16x16x32_bf16 v[2:5], v[174:177], v[210:213], v[2:5]
	v_mfma_f32_16x16x32_bf16 v[2:5], v[178:181], v[214:217], v[2:5]
	v_mfma_f32_16x16x32_bf16 v[18:21], v[178:181], v[206:209], v[18:21]
	v_mfma_f32_16x16x32_bf16 v[18:21], v[174:177], v[202:205], v[18:21]
	v_mfma_f32_16x16x32_bf16 v[34:37], v[174:177], v[190:193], v[34:37]
	v_mfma_f32_16x16x32_bf16 v[34:37], v[178:181], v[194:197], v[34:37]
	v_mfma_f32_16x16x32_bf16 v[50:53], v[178:181], v[186:189], v[50:53]
	v_mfma_f32_16x16x32_bf16 v[50:53], v[174:177], v[182:185], v[50:53]
	s_barrier
	s_add_i32 s78, 0, 0x18000
	s_add_i32 s79, 0, 0x1c000
	v_add_u32_e32 v142, s78, v199
	v_add_u32_e32 v162, s79, v199
	ds_read_b128 v[130:133], v142
	ds_read_b128 v[134:137], v142 offset:1024
	ds_read_b128 v[138:141], v142 offset:2048
	ds_read_b128 v[142:145], v142 offset:3072
	ds_read_b128 v[146:149], v162
	ds_read_b128 v[150:153], v162 offset:1024
	ds_read_b128 v[174:177], v162 offset:2048
	ds_read_b128 v[178:181], v162 offset:3072
	s_add_u32 s50, s56, 0x1000
	s_addc_u32 s51, s57, 0
	s_mov_b32 m0, s61
	v_lshl_add_u64 v[222:223], s[50:51], 0, v[154:155]
	ds_read_b128 v[182:185], v200 offset:32768
	ds_read_b128 v[186:189], v200 offset:33792
	ds_read_b128 v[190:193], v200 offset:34816
	ds_read_b128 v[194:197], v200 offset:35840
	ds_read_b128 v[202:205], v200 offset:36864
	ds_read_b128 v[206:209], v200 offset:37888
	ds_read_b128 v[210:213], v200 offset:38912
	ds_read_b128 v[214:217], v200 offset:39936
	global_load_lds_dwordx4 v[222:223], off
	v_lshl_add_u64 v[222:223], s[50:51], 0, v[158:159]
	s_mov_b32 m0, s62
	s_nop 0
	global_load_lds_dwordx4 v[222:223], off
	s_waitcnt vmcnt(8)
	s_waitcnt lgkmcnt(0)
	s_barrier
	v_mfma_f32_16x16x32_bf16 v[118:121], v[130:133], v[182:185], v[118:121]
	v_mfma_f32_16x16x32_bf16 v[118:121], v[134:137], v[186:189], v[118:121]
	v_mfma_f32_16x16x32_bf16 v[110:113], v[134:137], v[194:197], v[110:113]
	v_mfma_f32_16x16x32_bf16 v[110:113], v[130:133], v[190:193], v[110:113]
	v_mfma_f32_16x16x32_bf16 v[94:97], v[130:133], v[202:205], v[94:97]
	v_mfma_f32_16x16x32_bf16 v[94:97], v[134:137], v[206:209], v[94:97]
	v_mfma_f32_16x16x32_bf16 v[78:81], v[134:137], v[214:217], v[78:81]
	v_mfma_f32_16x16x32_bf16 v[78:81], v[130:133], v[210:213], v[78:81]
	v_mfma_f32_16x16x32_bf16 v[74:77], v[138:141], v[210:213], v[74:77]
	v_mfma_f32_16x16x32_bf16 v[74:77], v[142:145], v[214:217], v[74:77]
	v_mfma_f32_16x16x32_bf16 v[90:93], v[142:145], v[206:209], v[90:93]
	v_mfma_f32_16x16x32_bf16 v[90:93], v[138:141], v[202:205], v[90:93]
	v_mfma_f32_16x16x32_bf16 v[106:109], v[138:141], v[190:193], v[106:109]
	v_mfma_f32_16x16x32_bf16 v[106:109], v[142:145], v[194:197], v[106:109]
	v_mfma_f32_16x16x32_bf16 v[122:125], v[142:145], v[186:189], v[122:125]
	v_mfma_f32_16x16x32_bf16 v[122:125], v[138:141], v[182:185], v[122:125]
	v_mfma_f32_16x16x32_bf16 v[126:129], v[146:149], v[182:185], v[126:129]
	v_mfma_f32_16x16x32_bf16 v[126:129], v[150:153], v[186:189], v[126:129]
	v_mfma_f32_16x16x32_bf16 v[102:105], v[150:153], v[194:197], v[102:105]
	v_mfma_f32_16x16x32_bf16 v[102:105], v[146:149], v[190:193], v[102:105]
	v_mfma_f32_16x16x32_bf16 v[86:89], v[146:149], v[202:205], v[86:89]
	v_mfma_f32_16x16x32_bf16 v[86:89], v[150:153], v[206:209], v[86:89]
	v_mfma_f32_16x16x32_bf16 v[70:73], v[150:153], v[214:217], v[70:73]
	v_mfma_f32_16x16x32_bf16 v[70:73], v[146:149], v[210:213], v[70:73]
	v_mfma_f32_16x16x32_bf16 v[66:69], v[174:177], v[210:213], v[66:69]
	v_mfma_f32_16x16x32_bf16 v[66:69], v[178:181], v[214:217], v[66:69]
	v_mfma_f32_16x16x32_bf16 v[82:85], v[178:181], v[206:209], v[82:85]
	v_mfma_f32_16x16x32_bf16 v[82:85], v[174:177], v[202:205], v[82:85]
	v_mfma_f32_16x16x32_bf16 v[98:101], v[174:177], v[190:193], v[98:101]
	v_mfma_f32_16x16x32_bf16 v[98:101], v[178:181], v[194:197], v[98:101]
	v_mfma_f32_16x16x32_bf16 v[114:117], v[178:181], v[186:189], v[114:117]
	v_mfma_f32_16x16x32_bf16 v[114:117], v[174:177], v[182:185], v[114:117]
	s_barrier
	s_add_i32 s50, s78, s41
	v_lshl_add_u64 v[218:219], v[218:219], 0, s[14:15]
	s_mov_b32 m0, s50
	ds_read_b128 v[182:185], v200 offset:49152
	ds_read_b128 v[186:189], v200 offset:50176
	ds_read_b128 v[190:193], v200 offset:51200
	ds_read_b128 v[194:197], v200 offset:52224
	ds_read_b128 v[202:205], v200 offset:53248
	ds_read_b128 v[206:209], v200 offset:54272
	ds_read_b128 v[210:213], v200 offset:55296
	ds_read_b128 v[214:217], v200 offset:56320
	global_load_lds_dwordx4 v[218:219], off
	s_add_i32 m0, s50, 0x2000
	s_add_u32 s50, s54, 0x20080
	v_lshl_add_u64 v[218:219], v[220:221], 0, s[14:15]
	s_addc_u32 s51, s55, 0
	s_add_i32 s54, s79, s41
	global_load_lds_dwordx4 v[218:219], off
	v_lshl_add_u64 v[218:219], s[50:51], 0, v[156:157]
	s_mov_b32 m0, s54
	s_nop 0
	global_load_lds_dwordx4 v[218:219], off
	v_lshl_add_u64 v[218:219], s[50:51], 0, v[160:161]
	s_add_i32 m0, s54, 0x2000
	s_nop 0
	global_load_lds_dwordx4 v[218:219], off
	v_lshl_add_u64 v[218:219], s[52:53], 0, v[154:155]
	s_mov_b32 m0, s69
	s_nop 0
	global_load_lds_dwordx4 v[218:219], off
	v_lshl_add_u64 v[218:219], s[52:53], 0, v[158:159]
	s_mov_b32 m0, s70
	s_nop 0
	global_load_lds_dwordx4 v[218:219], off
	s_waitcnt vmcnt(8)
	s_waitcnt lgkmcnt(0)
	s_barrier
	v_mfma_f32_16x16x32_bf16 v[62:65], v[130:133], v[182:185], v[62:65]
	v_mfma_f32_16x16x32_bf16 v[62:65], v[134:137], v[186:189], v[62:65]
	v_mfma_f32_16x16x32_bf16 v[46:49], v[134:137], v[194:197], v[46:49]
	v_mfma_f32_16x16x32_bf16 v[46:49], v[130:133], v[190:193], v[46:49]
	v_mfma_f32_16x16x32_bf16 v[30:33], v[130:133], v[202:205], v[30:33]
	v_mfma_f32_16x16x32_bf16 v[30:33], v[134:137], v[206:209], v[30:33]
	v_mfma_f32_16x16x32_bf16 v[14:17], v[134:137], v[214:217], v[14:17]
	v_mfma_f32_16x16x32_bf16 v[14:17], v[130:133], v[210:213], v[14:17]
	v_mfma_f32_16x16x32_bf16 v[10:13], v[138:141], v[210:213], v[10:13]
	v_mfma_f32_16x16x32_bf16 v[10:13], v[142:145], v[214:217], v[10:13]
	v_mfma_f32_16x16x32_bf16 v[26:29], v[142:145], v[206:209], v[26:29]
	v_mfma_f32_16x16x32_bf16 v[26:29], v[138:141], v[202:205], v[26:29]
	v_mfma_f32_16x16x32_bf16 v[42:45], v[138:141], v[190:193], v[42:45]
	v_mfma_f32_16x16x32_bf16 v[42:45], v[142:145], v[194:197], v[42:45]
	v_mfma_f32_16x16x32_bf16 v[58:61], v[142:145], v[186:189], v[58:61]
	v_mfma_f32_16x16x32_bf16 v[58:61], v[138:141], v[182:185], v[58:61]
	v_mfma_f32_16x16x32_bf16 v[54:57], v[146:149], v[182:185], v[54:57]
	v_mfma_f32_16x16x32_bf16 v[54:57], v[150:153], v[186:189], v[54:57]
	v_mfma_f32_16x16x32_bf16 v[38:41], v[150:153], v[194:197], v[38:41]
	v_mfma_f32_16x16x32_bf16 v[38:41], v[146:149], v[190:193], v[38:41]
	v_mfma_f32_16x16x32_bf16 v[22:25], v[146:149], v[202:205], v[22:25]
	v_mfma_f32_16x16x32_bf16 v[22:25], v[150:153], v[206:209], v[22:25]
	v_mfma_f32_16x16x32_bf16 v[6:9], v[150:153], v[214:217], v[6:9]
	v_mfma_f32_16x16x32_bf16 v[6:9], v[146:149], v[210:213], v[6:9]
	v_mfma_f32_16x16x32_bf16 v[2:5], v[174:177], v[210:213], v[2:5]
	v_mfma_f32_16x16x32_bf16 v[2:5], v[178:181], v[214:217], v[2:5]
	v_mfma_f32_16x16x32_bf16 v[18:21], v[178:181], v[206:209], v[18:21]
	v_mfma_f32_16x16x32_bf16 v[18:21], v[174:177], v[202:205], v[18:21]
	v_mfma_f32_16x16x32_bf16 v[34:37], v[174:177], v[190:193], v[34:37]
	v_mfma_f32_16x16x32_bf16 v[34:37], v[178:181], v[194:197], v[34:37]
	v_mfma_f32_16x16x32_bf16 v[50:53], v[178:181], v[186:189], v[50:53]
	v_mfma_f32_16x16x32_bf16 v[50:53], v[174:177], v[182:185], v[50:53]
	s_barrier
	s_add_u32 s23, s23, 0x100
	s_addc_u32 s25, s25, 0
	s_add_u32 s34, s34, 0x800000
	s_addc_u32 s35, s35, 0
	s_cmp_ge_i32 s31, s67
	s_mov_b32 s52, s31
	s_cbranch_scc0 .LBB0_599

.LBB0_740:
	v_add_u32_e32 v144, s88, v188
	v_add_u32_e32 v160, s89, v188
	ds_read_b128 v[132:135], v144
	ds_read_b128 v[136:139], v144 offset:1024
	ds_read_b128 v[140:143], v144 offset:2048
	ds_read_b128 v[144:147], v144 offset:3072
	ds_read_b128 v[148:151], v160
	ds_read_b128 v[152:155], v160 offset:1024
	ds_read_b128 v[156:159], v160 offset:2048
	ds_read_b128 v[184:187], v160 offset:3072
	s_add_i32 s92, s55, 2
	s_add_u32 s50, s60, 0x3fc000
	s_addc_u32 s51, s61, 0
	s_cmp_eq_u32 s87, s55
	s_cselect_b32 s70, s64, s50
	s_cselect_b32 s71, s65, s51
	s_cselect_b32 s69, s67, s53
	s_cselect_b32 s68, s66, s13
	s_add_u32 s62, s70, 0x400000
	s_addc_u32 s63, s71, 0
	v_lshl_add_u64 v[160:161], s[60:61], 0, v[176:177]
	s_add_i32 m0, s77, 0xc000
	ds_read_b128 v[192:195], v189
	ds_read_b128 v[196:199], v189 offset:1024
	ds_read_b128 v[200:203], v189 offset:2048
	ds_read_b128 v[204:207], v189 offset:3072
	ds_read_b128 v[208:211], v189 offset:4096
	ds_read_b128 v[212:215], v189 offset:5120
	ds_read_b128 v[216:219], v189 offset:6144
	ds_read_b128 v[220:223], v189 offset:7168
	global_load_lds_dwordx4 v[160:161], off
	v_lshl_add_u64 v[160:161], s[60:61], 0, v[178:179]
	s_add_i32 m0, s77, 0xe000
	s_nop 0
	global_load_lds_dwordx4 v[160:161], off
	s_waitcnt vmcnt(8)
	s_waitcnt lgkmcnt(0)
	s_barrier
	v_mfma_f32_16x16x32_bf16 v[30:33], v[132:135], v[192:195], v[30:33]
	v_mfma_f32_16x16x32_bf16 v[30:33], v[136:139], v[196:199], v[30:33]
	v_mfma_f32_16x16x32_bf16 v[86:89], v[136:139], v[204:207], v[86:89]
	v_mfma_f32_16x16x32_bf16 v[86:89], v[132:135], v[200:203], v[86:89]
	v_mfma_f32_16x16x32_bf16 v[94:97], v[132:135], v[208:211], v[94:97]
	v_mfma_f32_16x16x32_bf16 v[94:97], v[136:139], v[212:215], v[94:97]
	v_mfma_f32_16x16x32_bf16 v[90:93], v[136:139], v[220:223], v[90:93]
	v_mfma_f32_16x16x32_bf16 v[90:93], v[132:135], v[216:219], v[90:93]
	v_mfma_f32_16x16x32_bf16 v[78:81], v[140:143], v[216:219], v[78:81]
	v_mfma_f32_16x16x32_bf16 v[78:81], v[144:147], v[220:223], v[78:81]
	v_mfma_f32_16x16x32_bf16 v[82:85], v[144:147], v[212:215], v[82:85]
	v_mfma_f32_16x16x32_bf16 v[82:85], v[140:143], v[208:211], v[82:85]
	v_mfma_f32_16x16x32_bf16 v[66:69], v[140:143], v[200:203], v[66:69]
	v_mfma_f32_16x16x32_bf16 v[66:69], v[144:147], v[204:207], v[66:69]
	v_mfma_f32_16x16x32_bf16 v[26:29], v[144:147], v[196:199], v[26:29]
	v_mfma_f32_16x16x32_bf16 v[26:29], v[140:143], v[192:195], v[26:29]
	v_mfma_f32_16x16x32_bf16 v[50:53], v[148:151], v[192:195], v[50:53]
	v_mfma_f32_16x16x32_bf16 v[50:53], v[152:155], v[196:199], v[50:53]
	v_mfma_f32_16x16x32_bf16 v[14:17], v[152:155], v[204:207], v[14:17]
	v_mfma_f32_16x16x32_bf16 v[14:17], v[148:151], v[200:203], v[14:17]
	v_mfma_f32_16x16x32_bf16 v[22:25], v[148:151], v[208:211], v[22:25]
	v_mfma_f32_16x16x32_bf16 v[22:25], v[152:155], v[212:215], v[22:25]
	v_mfma_f32_16x16x32_bf16 v[18:21], v[152:155], v[220:223], v[18:21]
	v_mfma_f32_16x16x32_bf16 v[18:21], v[148:151], v[216:219], v[18:21]
	v_mfma_f32_16x16x32_bf16 v[6:9], v[156:159], v[216:219], v[6:9]
	v_mfma_f32_16x16x32_bf16 v[6:9], v[184:187], v[220:223], v[6:9]
	v_mfma_f32_16x16x32_bf16 v[10:13], v[184:187], v[212:215], v[10:13]
	v_mfma_f32_16x16x32_bf16 v[10:13], v[156:159], v[208:211], v[10:13]
	v_mfma_f32_16x16x32_bf16 v[2:5], v[156:159], v[200:203], v[2:5]
	v_mfma_f32_16x16x32_bf16 v[2:5], v[184:187], v[204:207], v[2:5]
	v_mfma_f32_16x16x32_bf16 v[42:45], v[184:187], v[196:199], v[42:45]
	v_mfma_f32_16x16x32_bf16 v[42:45], v[156:159], v[192:195], v[42:45]
	s_barrier
	s_add_i32 s50, s88, s76
	v_lshl_add_u64 v[160:161], s[68:69], 0, v[164:165]
	s_mov_b32 m0, s50
	ds_read_b128 v[192:195], v189 offset:16384
	ds_read_b128 v[196:199], v189 offset:17408
	ds_read_b128 v[200:203], v189 offset:18432
	ds_read_b128 v[204:207], v189 offset:19456
	ds_read_b128 v[208:211], v189 offset:20480
	ds_read_b128 v[212:215], v189 offset:21504
	ds_read_b128 v[216:219], v189 offset:22528
	ds_read_b128 v[220:223], v189 offset:23552
	global_load_lds_dwordx4 v[160:161], off
	s_add_i32 m0, s50, 0x2000
	s_add_u32 s50, s68, 0x10000
	v_lshl_add_u64 v[224:225], s[68:69], 0, v[168:169]
	s_addc_u32 s51, s69, 0
	s_add_i32 s55, s89, s76
	global_load_lds_dwordx4 v[224:225], off
	v_lshl_add_u64 v[226:227], s[50:51], 0, v[164:165]
	s_mov_b32 m0, s55
	s_nop 0
	global_load_lds_dwordx4 v[226:227], off
	v_lshl_add_u64 v[226:227], s[50:51], 0, v[168:169]
	s_add_i32 m0, s55, 0x2000
	s_nop 0
	global_load_lds_dwordx4 v[226:227], off
	v_lshl_add_u64 v[226:227], s[70:71], 0, v[162:163]
	s_mov_b32 m0, s77
	s_nop 0
	global_load_lds_dwordx4 v[226:227], off
	v_lshl_add_u64 v[226:227], s[70:71], 0, v[166:167]
	s_mov_b32 m0, s78
	s_nop 0
	global_load_lds_dwordx4 v[226:227], off
	s_waitcnt vmcnt(8)
	s_waitcnt lgkmcnt(0)
	s_barrier
	v_mfma_f32_16x16x32_bf16 v[118:121], v[132:135], v[192:195], v[118:121]
	v_mfma_f32_16x16x32_bf16 v[118:121], v[136:139], v[196:199], v[118:121]
	v_mfma_f32_16x16x32_bf16 v[114:117], v[136:139], v[204:207], v[114:117]
	v_mfma_f32_16x16x32_bf16 v[114:117], v[132:135], v[200:203], v[114:117]
	v_mfma_f32_16x16x32_bf16 v[126:129], v[132:135], v[208:211], v[126:129]
	v_mfma_f32_16x16x32_bf16 v[126:129], v[136:139], v[212:215], v[126:129]
	v_mfma_f32_16x16x32_bf16 v[122:125], v[136:139], v[220:223], v[122:125]
	v_mfma_f32_16x16x32_bf16 v[122:125], v[132:135], v[216:219], v[122:125]
	v_mfma_f32_16x16x32_bf16 v[106:109], v[140:143], v[216:219], v[106:109]
	v_mfma_f32_16x16x32_bf16 v[106:109], v[144:147], v[220:223], v[106:109]
	v_mfma_f32_16x16x32_bf16 v[110:113], v[144:147], v[212:215], v[110:113]
	v_mfma_f32_16x16x32_bf16 v[110:113], v[140:143], v[208:211], v[110:113]
	v_mfma_f32_16x16x32_bf16 v[98:101], v[140:143], v[200:203], v[98:101]
	v_mfma_f32_16x16x32_bf16 v[98:101], v[144:147], v[204:207], v[98:101]
	v_mfma_f32_16x16x32_bf16 v[102:105], v[144:147], v[196:199], v[102:105]
	v_mfma_f32_16x16x32_bf16 v[102:105], v[140:143], v[192:195], v[102:105]
	v_mfma_f32_16x16x32_bf16 v[62:65], v[148:151], v[192:195], v[62:65]
	v_mfma_f32_16x16x32_bf16 v[62:65], v[152:155], v[196:199], v[62:65]
	v_mfma_f32_16x16x32_bf16 v[58:61], v[152:155], v[204:207], v[58:61]
	v_mfma_f32_16x16x32_bf16 v[58:61], v[148:151], v[200:203], v[58:61]
	v_mfma_f32_16x16x32_bf16 v[74:77], v[148:151], v[208:211], v[74:77]
	v_mfma_f32_16x16x32_bf16 v[74:77], v[152:155], v[212:215], v[74:77]
	v_mfma_f32_16x16x32_bf16 v[70:73], v[152:155], v[220:223], v[70:73]
	v_mfma_f32_16x16x32_bf16 v[70:73], v[148:151], v[216:219], v[70:73]
	v_mfma_f32_16x16x32_bf16 v[46:49], v[156:159], v[216:219], v[46:49]
	v_mfma_f32_16x16x32_bf16 v[46:49], v[184:187], v[220:223], v[46:49]
	v_mfma_f32_16x16x32_bf16 v[54:57], v[184:187], v[212:215], v[54:57]
	v_mfma_f32_16x16x32_bf16 v[54:57], v[156:159], v[208:211], v[54:57]
	v_mfma_f32_16x16x32_bf16 v[34:37], v[156:159], v[200:203], v[34:37]
	v_mfma_f32_16x16x32_bf16 v[34:37], v[184:187], v[204:207], v[34:37]
	v_mfma_f32_16x16x32_bf16 v[38:41], v[184:187], v[196:199], v[38:41]
	v_mfma_f32_16x16x32_bf16 v[38:41], v[156:159], v[192:195], v[38:41]
	s_barrier
	s_add_i32 s55, 0, 0x18000
	s_add_i32 s93, 0, 0x1c000
	v_add_u32_e32 v144, s55, v188
	v_add_u32_e32 v184, s93, v188
	ds_read_b128 v[132:135], v144
	ds_read_b128 v[136:139], v144 offset:1024
	ds_read_b128 v[140:143], v144 offset:2048
	ds_read_b128 v[144:147], v144 offset:3072
	ds_read_b128 v[148:151], v184
	ds_read_b128 v[152:155], v184 offset:1024
	ds_read_b128 v[156:159], v184 offset:2048
	ds_read_b128 v[184:187], v184 offset:3072
	s_add_u32 s50, s70, 0x4000
	s_addc_u32 s51, s71, 0
	s_mov_b32 m0, s79
	v_lshl_add_u64 v[226:227], s[50:51], 0, v[162:163]
	ds_read_b128 v[192:195], v189 offset:32768
	ds_read_b128 v[196:199], v189 offset:33792
	ds_read_b128 v[200:203], v189 offset:34816
	ds_read_b128 v[204:207], v189 offset:35840
	ds_read_b128 v[208:211], v189 offset:36864
	ds_read_b128 v[212:215], v189 offset:37888
	ds_read_b128 v[216:219], v189 offset:38912
	ds_read_b128 v[220:223], v189 offset:39936
	global_load_lds_dwordx4 v[226:227], off
	v_lshl_add_u64 v[226:227], s[50:51], 0, v[166:167]
	s_mov_b32 m0, s80
	s_nop 0
	global_load_lds_dwordx4 v[226:227], off
	s_waitcnt vmcnt(8)
	s_waitcnt lgkmcnt(0)
	s_barrier
	v_mfma_f32_16x16x32_bf16 v[30:33], v[132:135], v[192:195], v[30:33]
	v_mfma_f32_16x16x32_bf16 v[30:33], v[136:139], v[196:199], v[30:33]
	v_mfma_f32_16x16x32_bf16 v[86:89], v[136:139], v[204:207], v[86:89]
	v_mfma_f32_16x16x32_bf16 v[86:89], v[132:135], v[200:203], v[86:89]
	v_mfma_f32_16x16x32_bf16 v[94:97], v[132:135], v[208:211], v[94:97]
	v_mfma_f32_16x16x32_bf16 v[94:97], v[136:139], v[212:215], v[94:97]
	v_mfma_f32_16x16x32_bf16 v[90:93], v[136:139], v[220:223], v[90:93]
	v_mfma_f32_16x16x32_bf16 v[90:93], v[132:135], v[216:219], v[90:93]
	v_mfma_f32_16x16x32_bf16 v[78:81], v[140:143], v[216:219], v[78:81]
	v_mfma_f32_16x16x32_bf16 v[78:81], v[144:147], v[220:223], v[78:81]
	v_mfma_f32_16x16x32_bf16 v[82:85], v[144:147], v[212:215], v[82:85]
	v_mfma_f32_16x16x32_bf16 v[82:85], v[140:143], v[208:211], v[82:85]
	v_mfma_f32_16x16x32_bf16 v[66:69], v[140:143], v[200:203], v[66:69]
	v_mfma_f32_16x16x32_bf16 v[66:69], v[144:147], v[204:207], v[66:69]
	v_mfma_f32_16x16x32_bf16 v[26:29], v[144:147], v[196:199], v[26:29]
	v_mfma_f32_16x16x32_bf16 v[26:29], v[140:143], v[192:195], v[26:29]
	v_mfma_f32_16x16x32_bf16 v[50:53], v[148:151], v[192:195], v[50:53]
	v_mfma_f32_16x16x32_bf16 v[50:53], v[152:155], v[196:199], v[50:53]
	v_mfma_f32_16x16x32_bf16 v[14:17], v[152:155], v[204:207], v[14:17]
	v_mfma_f32_16x16x32_bf16 v[14:17], v[148:151], v[200:203], v[14:17]
	v_mfma_f32_16x16x32_bf16 v[22:25], v[148:151], v[208:211], v[22:25]
	v_mfma_f32_16x16x32_bf16 v[22:25], v[152:155], v[212:215], v[22:25]
	v_mfma_f32_16x16x32_bf16 v[18:21], v[152:155], v[220:223], v[18:21]
	v_mfma_f32_16x16x32_bf16 v[18:21], v[148:151], v[216:219], v[18:21]
	v_mfma_f32_16x16x32_bf16 v[6:9], v[156:159], v[216:219], v[6:9]
	v_mfma_f32_16x16x32_bf16 v[6:9], v[184:187], v[220:223], v[6:9]
	v_mfma_f32_16x16x32_bf16 v[10:13], v[184:187], v[212:215], v[10:13]
	v_mfma_f32_16x16x32_bf16 v[10:13], v[156:159], v[208:211], v[10:13]
	v_mfma_f32_16x16x32_bf16 v[2:5], v[156:159], v[200:203], v[2:5]
	v_mfma_f32_16x16x32_bf16 v[2:5], v[184:187], v[204:207], v[2:5]
	v_mfma_f32_16x16x32_bf16 v[42:45], v[184:187], v[196:199], v[42:45]
	v_mfma_f32_16x16x32_bf16 v[42:45], v[156:159], v[192:195], v[42:45]
	s_barrier
	s_add_i32 s50, s55, s76
	v_lshl_add_u64 v[160:161], v[160:161], 0, s[14:15]
	s_mov_b32 m0, s50
	ds_read_b128 v[192:195], v189 offset:49152
	ds_read_b128 v[196:199], v189 offset:50176
	ds_read_b128 v[200:203], v189 offset:51200
	ds_read_b128 v[204:207], v189 offset:52224
	ds_read_b128 v[208:211], v189 offset:53248
	ds_read_b128 v[212:215], v189 offset:54272
	ds_read_b128 v[216:219], v189 offset:55296
	ds_read_b128 v[220:223], v189 offset:56320
	global_load_lds_dwordx4 v[160:161], off
	s_add_i32 m0, s50, 0x2000
	s_add_u32 s50, s68, 0x10080
	v_lshl_add_u64 v[160:161], v[224:225], 0, s[14:15]
	s_addc_u32 s51, s69, 0
	s_add_i32 s55, s93, s76
	global_load_lds_dwordx4 v[160:161], off
	v_lshl_add_u64 v[160:161], s[50:51], 0, v[164:165]
	s_mov_b32 m0, s55
	s_nop 0
	global_load_lds_dwordx4 v[160:161], off
	v_lshl_add_u64 v[160:161], s[50:51], 0, v[168:169]
	s_add_i32 m0, s55, 0x2000
	s_nop 0
	global_load_lds_dwordx4 v[160:161], off
	v_lshl_add_u64 v[160:161], s[62:63], 0, v[162:163]
	s_mov_b32 m0, s84
	s_nop 0
	global_load_lds_dwordx4 v[160:161], off
	v_lshl_add_u64 v[160:161], s[62:63], 0, v[166:167]
	s_mov_b32 m0, s85
	s_nop 0
	global_load_lds_dwordx4 v[160:161], off
	s_waitcnt vmcnt(8)
	s_waitcnt lgkmcnt(0)
	s_barrier
	v_mfma_f32_16x16x32_bf16 v[118:121], v[132:135], v[192:195], v[118:121]
	v_mfma_f32_16x16x32_bf16 v[118:121], v[136:139], v[196:199], v[118:121]
	v_mfma_f32_16x16x32_bf16 v[114:117], v[136:139], v[204:207], v[114:117]
	v_mfma_f32_16x16x32_bf16 v[114:117], v[132:135], v[200:203], v[114:117]
	v_mfma_f32_16x16x32_bf16 v[126:129], v[132:135], v[208:211], v[126:129]
	v_mfma_f32_16x16x32_bf16 v[126:129], v[136:139], v[212:215], v[126:129]
	v_mfma_f32_16x16x32_bf16 v[122:125], v[136:139], v[220:223], v[122:125]
	v_mfma_f32_16x16x32_bf16 v[122:125], v[132:135], v[216:219], v[122:125]
	v_mfma_f32_16x16x32_bf16 v[106:109], v[140:143], v[216:219], v[106:109]
	v_mfma_f32_16x16x32_bf16 v[106:109], v[144:147], v[220:223], v[106:109]
	v_mfma_f32_16x16x32_bf16 v[110:113], v[144:147], v[212:215], v[110:113]
	v_mfma_f32_16x16x32_bf16 v[110:113], v[140:143], v[208:211], v[110:113]
	v_mfma_f32_16x16x32_bf16 v[98:101], v[140:143], v[200:203], v[98:101]
	v_mfma_f32_16x16x32_bf16 v[98:101], v[144:147], v[204:207], v[98:101]
	v_mfma_f32_16x16x32_bf16 v[102:105], v[144:147], v[196:199], v[102:105]
	v_mfma_f32_16x16x32_bf16 v[102:105], v[140:143], v[192:195], v[102:105]
	v_mfma_f32_16x16x32_bf16 v[62:65], v[148:151], v[192:195], v[62:65]
	v_mfma_f32_16x16x32_bf16 v[62:65], v[152:155], v[196:199], v[62:65]
	v_mfma_f32_16x16x32_bf16 v[58:61], v[152:155], v[204:207], v[58:61]
	v_mfma_f32_16x16x32_bf16 v[58:61], v[148:151], v[200:203], v[58:61]
	v_mfma_f32_16x16x32_bf16 v[74:77], v[148:151], v[208:211], v[74:77]
	v_mfma_f32_16x16x32_bf16 v[74:77], v[152:155], v[212:215], v[74:77]
	v_mfma_f32_16x16x32_bf16 v[70:73], v[152:155], v[220:223], v[70:73]
	v_mfma_f32_16x16x32_bf16 v[70:73], v[148:151], v[216:219], v[70:73]
	v_mfma_f32_16x16x32_bf16 v[46:49], v[156:159], v[216:219], v[46:49]
	v_mfma_f32_16x16x32_bf16 v[46:49], v[184:187], v[220:223], v[46:49]
	v_mfma_f32_16x16x32_bf16 v[54:57], v[184:187], v[212:215], v[54:57]
	v_mfma_f32_16x16x32_bf16 v[54:57], v[156:159], v[208:211], v[54:57]
	v_mfma_f32_16x16x32_bf16 v[34:37], v[156:159], v[200:203], v[34:37]
	v_mfma_f32_16x16x32_bf16 v[34:37], v[184:187], v[204:207], v[34:37]
	v_mfma_f32_16x16x32_bf16 v[38:41], v[184:187], v[196:199], v[38:41]
	v_mfma_f32_16x16x32_bf16 v[38:41], v[156:159], v[192:195], v[38:41]
	s_barrier
	s_add_u32 s13, s13, 0x100
	s_addc_u32 s53, s53, 0
	s_add_u32 s60, s60, 0x800000
	s_addc_u32 s61, s61, 0
	s_cmp_ge_i32 s92, s83
	s_cbranch_scc0 .LBB0_738

.LBB0_872:
	v_add_u32_e32 v162, s73, v140
	v_add_u32_e32 v178, s74, v140
	ds_read_b128 v[150:153], v162
	ds_read_b128 v[154:157], v162 offset:1024
	ds_read_b128 v[158:161], v162 offset:2048
	ds_read_b128 v[162:165], v162 offset:3072
	ds_read_b128 v[166:169], v178
	ds_read_b128 v[170:173], v178 offset:1024
	ds_read_b128 v[174:177], v178 offset:2048
	ds_read_b128 v[178:181], v178 offset:3072
	s_add_i32 s77, s52, 2
	s_add_u32 s50, s34, 0xfffc0080
	s_addc_u32 s51, s35, -1
	s_cmp_eq_u32 s70, s52
	s_cselect_b32 s52, s30, s21
	s_cselect_b32 s55, s29, s51
	s_cselect_b32 s54, s28, s50
	s_cselect_b32 s53, s31, s23
	v_lshl_add_u64 v[214:215], s[34:35], 0, v[132:133]
	s_add_i32 m0, s60, 0xc000
	ds_read_b128 v[182:185], v149
	ds_read_b128 v[186:189], v149 offset:1024
	ds_read_b128 v[190:193], v149 offset:2048
	ds_read_b128 v[194:197], v149 offset:3072
	ds_read_b128 v[198:201], v149 offset:4096
	ds_read_b128 v[202:205], v149 offset:5120
	ds_read_b128 v[206:209], v149 offset:6144
	ds_read_b128 v[210:213], v149 offset:7168
	global_load_lds_dwordx4 v[214:215], off
	v_lshl_add_u64 v[214:215], s[34:35], 0, v[134:135]
	s_add_i32 m0, s60, 0xe000
	s_nop 0
	global_load_lds_dwordx4 v[214:215], off
	s_waitcnt vmcnt(8)
	s_waitcnt lgkmcnt(0)
	s_barrier
	v_mfma_f32_16x16x32_bf16 v[78:81], v[150:153], v[182:185], v[78:81]
	v_mfma_f32_16x16x32_bf16 v[78:81], v[154:157], v[186:189], v[78:81]
	v_mfma_f32_16x16x32_bf16 v[66:69], v[154:157], v[194:197], v[66:69]
	v_mfma_f32_16x16x32_bf16 v[66:69], v[150:153], v[190:193], v[66:69]
	v_mfma_f32_16x16x32_bf16 v[70:73], v[150:153], v[198:201], v[70:73]
	v_mfma_f32_16x16x32_bf16 v[70:73], v[154:157], v[202:205], v[70:73]
	v_mfma_f32_16x16x32_bf16 v[74:77], v[154:157], v[210:213], v[74:77]
	v_mfma_f32_16x16x32_bf16 v[74:77], v[150:153], v[206:209], v[74:77]
	v_mfma_f32_16x16x32_bf16 v[10:13], v[158:161], v[206:209], v[10:13]
	v_mfma_f32_16x16x32_bf16 v[10:13], v[162:165], v[210:213], v[10:13]
	v_mfma_f32_16x16x32_bf16 v[6:9], v[162:165], v[202:205], v[6:9]
	v_mfma_f32_16x16x32_bf16 v[6:9], v[158:161], v[198:201], v[6:9]
	v_mfma_f32_16x16x32_bf16 v[2:5], v[158:161], v[190:193], v[2:5]
	v_mfma_f32_16x16x32_bf16 v[2:5], v[162:165], v[194:197], v[2:5]
	v_mfma_f32_16x16x32_bf16 v[14:17], v[162:165], v[186:189], v[14:17]
	v_mfma_f32_16x16x32_bf16 v[14:17], v[158:161], v[182:185], v[14:17]
	v_mfma_f32_16x16x32_bf16 v[98:101], v[166:169], v[182:185], v[98:101]
	v_mfma_f32_16x16x32_bf16 v[98:101], v[170:173], v[186:189], v[98:101]
	v_mfma_f32_16x16x32_bf16 v[82:85], v[170:173], v[194:197], v[82:85]
	v_mfma_f32_16x16x32_bf16 v[82:85], v[166:169], v[190:193], v[82:85]
	v_mfma_f32_16x16x32_bf16 v[86:89], v[166:169], v[198:201], v[86:89]
	v_mfma_f32_16x16x32_bf16 v[86:89], v[170:173], v[202:205], v[86:89]
	v_mfma_f32_16x16x32_bf16 v[94:97], v[170:173], v[210:213], v[94:97]
	v_mfma_f32_16x16x32_bf16 v[94:97], v[166:169], v[206:209], v[94:97]
	v_mfma_f32_16x16x32_bf16 v[30:33], v[174:177], v[206:209], v[30:33]
	v_mfma_f32_16x16x32_bf16 v[30:33], v[178:181], v[210:213], v[30:33]
	v_mfma_f32_16x16x32_bf16 v[22:25], v[178:181], v[202:205], v[22:25]
	v_mfma_f32_16x16x32_bf16 v[22:25], v[174:177], v[198:201], v[22:25]
	v_mfma_f32_16x16x32_bf16 v[18:21], v[174:177], v[190:193], v[18:21]
	v_mfma_f32_16x16x32_bf16 v[18:21], v[178:181], v[194:197], v[18:21]
	v_mfma_f32_16x16x32_bf16 v[34:37], v[178:181], v[186:189], v[34:37]
	v_mfma_f32_16x16x32_bf16 v[34:37], v[174:177], v[182:185], v[34:37]
	s_barrier
	s_add_i32 s50, s73, s15
	v_lshl_add_u64 v[214:215], s[52:53], 0, v[228:229]
	s_mov_b32 m0, s50
	ds_read_b128 v[182:185], v149 offset:16384
	ds_read_b128 v[186:189], v149 offset:17408
	ds_read_b128 v[190:193], v149 offset:18432
	ds_read_b128 v[194:197], v149 offset:19456
	ds_read_b128 v[198:201], v149 offset:20480
	ds_read_b128 v[202:205], v149 offset:21504
	ds_read_b128 v[206:209], v149 offset:22528
	ds_read_b128 v[210:213], v149 offset:23552
	global_load_lds_dwordx4 v[214:215], off
	s_add_i32 m0, s50, 0x2000
	s_add_u32 s50, s52, 0x40000
	v_lshl_add_u64 v[216:217], s[52:53], 0, v[232:233]
	s_addc_u32 s51, s53, 0
	s_add_i32 s78, s74, s15
	global_load_lds_dwordx4 v[216:217], off
	v_lshl_add_u64 v[218:219], s[50:51], 0, v[228:229]
	s_mov_b32 m0, s78
	v_lshl_add_u64 v[220:221], s[54:55], 0, v[230:231]
	global_load_lds_dwordx4 v[218:219], off
	v_lshl_add_u64 v[218:219], s[50:51], 0, v[232:233]
	s_add_i32 m0, s78, 0x2000
	s_nop 0
	global_load_lds_dwordx4 v[218:219], off
	v_lshl_add_u64 v[218:219], s[54:55], 0, v[226:227]
	s_mov_b32 m0, s60
	s_nop 0
	global_load_lds_dwordx4 v[218:219], off
	s_mov_b32 m0, s61
	s_nop 0
	global_load_lds_dwordx4 v[220:221], off
	s_waitcnt vmcnt(8)
	s_waitcnt lgkmcnt(0)
	s_barrier
	v_mfma_f32_16x16x32_bf16 v[90:93], v[150:153], v[182:185], v[90:93]
	v_mfma_f32_16x16x32_bf16 v[90:93], v[154:157], v[186:189], v[90:93]
	v_mfma_f32_16x16x32_bf16 v[102:105], v[154:157], v[194:197], v[102:105]
	v_mfma_f32_16x16x32_bf16 v[102:105], v[150:153], v[190:193], v[102:105]
	v_mfma_f32_16x16x32_bf16 v[106:109], v[150:153], v[198:201], v[106:109]
	v_mfma_f32_16x16x32_bf16 v[106:109], v[154:157], v[202:205], v[106:109]
	v_mfma_f32_16x16x32_bf16 v[110:113], v[154:157], v[210:213], v[110:113]
	v_mfma_f32_16x16x32_bf16 v[110:113], v[150:153], v[206:209], v[110:113]
	v_mfma_f32_16x16x32_bf16 v[46:49], v[158:161], v[206:209], v[46:49]
	v_mfma_f32_16x16x32_bf16 v[46:49], v[162:165], v[210:213], v[46:49]
	v_mfma_f32_16x16x32_bf16 v[42:45], v[162:165], v[202:205], v[42:45]
	v_mfma_f32_16x16x32_bf16 v[42:45], v[158:161], v[198:201], v[42:45]
	v_mfma_f32_16x16x32_bf16 v[38:41], v[158:161], v[190:193], v[38:41]
	v_mfma_f32_16x16x32_bf16 v[38:41], v[162:165], v[194:197], v[38:41]
	v_mfma_f32_16x16x32_bf16 v[26:29], v[162:165], v[186:189], v[26:29]
	v_mfma_f32_16x16x32_bf16 v[26:29], v[158:161], v[182:185], v[26:29]
	v_mfma_f32_16x16x32_bf16 v[114:117], v[166:169], v[182:185], v[114:117]
	v_mfma_f32_16x16x32_bf16 v[114:117], v[170:173], v[186:189], v[114:117]
	v_mfma_f32_16x16x32_bf16 v[118:121], v[170:173], v[194:197], v[118:121]
	v_mfma_f32_16x16x32_bf16 v[118:121], v[166:169], v[190:193], v[118:121]
	v_mfma_f32_16x16x32_bf16 v[122:125], v[166:169], v[198:201], v[122:125]
	v_mfma_f32_16x16x32_bf16 v[122:125], v[170:173], v[202:205], v[122:125]
	v_mfma_f32_16x16x32_bf16 v[126:129], v[170:173], v[210:213], v[126:129]
	v_mfma_f32_16x16x32_bf16 v[126:129], v[166:169], v[206:209], v[126:129]
	v_mfma_f32_16x16x32_bf16 v[62:65], v[174:177], v[206:209], v[62:65]
	v_mfma_f32_16x16x32_bf16 v[62:65], v[178:181], v[210:213], v[62:65]
	v_mfma_f32_16x16x32_bf16 v[58:61], v[178:181], v[202:205], v[58:61]
	v_mfma_f32_16x16x32_bf16 v[58:61], v[174:177], v[198:201], v[58:61]
	v_mfma_f32_16x16x32_bf16 v[54:57], v[174:177], v[190:193], v[54:57]
	v_mfma_f32_16x16x32_bf16 v[54:57], v[178:181], v[194:197], v[54:57]
	v_mfma_f32_16x16x32_bf16 v[50:53], v[178:181], v[186:189], v[50:53]
	v_mfma_f32_16x16x32_bf16 v[50:53], v[174:177], v[182:185], v[50:53]
	s_barrier
	s_add_i32 s78, 0, 0x18000
	s_add_i32 s79, 0, 0x1c000
	v_add_u32_e32 v162, s78, v140
	v_add_u32_e32 v178, s79, v140
	ds_read_b128 v[150:153], v162
	ds_read_b128 v[154:157], v162 offset:1024
	ds_read_b128 v[158:161], v162 offset:2048
	ds_read_b128 v[162:165], v162 offset:3072
	ds_read_b128 v[166:169], v178
	ds_read_b128 v[170:173], v178 offset:1024
	ds_read_b128 v[174:177], v178 offset:2048
	ds_read_b128 v[178:181], v178 offset:3072
	s_add_u32 s50, s54, 0x40000
	s_addc_u32 s51, s55, 0
	s_mov_b32 m0, s62
	v_lshl_add_u64 v[222:223], s[50:51], 0, v[226:227]
	ds_read_b128 v[182:185], v149 offset:32768
	ds_read_b128 v[186:189], v149 offset:33792
	ds_read_b128 v[190:193], v149 offset:34816
	ds_read_b128 v[194:197], v149 offset:35840
	ds_read_b128 v[198:201], v149 offset:36864
	ds_read_b128 v[202:205], v149 offset:37888
	ds_read_b128 v[206:209], v149 offset:38912
	ds_read_b128 v[210:213], v149 offset:39936
	global_load_lds_dwordx4 v[222:223], off
	v_lshl_add_u64 v[222:223], s[50:51], 0, v[230:231]
	s_mov_b32 m0, s63
	s_nop 0
	global_load_lds_dwordx4 v[222:223], off
	s_waitcnt vmcnt(8)
	s_waitcnt lgkmcnt(0)
	s_barrier
	v_mfma_f32_16x16x32_bf16 v[78:81], v[150:153], v[182:185], v[78:81]
	v_mfma_f32_16x16x32_bf16 v[78:81], v[154:157], v[186:189], v[78:81]
	v_mfma_f32_16x16x32_bf16 v[66:69], v[154:157], v[194:197], v[66:69]
	v_mfma_f32_16x16x32_bf16 v[66:69], v[150:153], v[190:193], v[66:69]
	v_mfma_f32_16x16x32_bf16 v[70:73], v[150:153], v[198:201], v[70:73]
	v_mfma_f32_16x16x32_bf16 v[70:73], v[154:157], v[202:205], v[70:73]
	v_mfma_f32_16x16x32_bf16 v[74:77], v[154:157], v[210:213], v[74:77]
	v_mfma_f32_16x16x32_bf16 v[74:77], v[150:153], v[206:209], v[74:77]
	v_mfma_f32_16x16x32_bf16 v[10:13], v[158:161], v[206:209], v[10:13]
	v_mfma_f32_16x16x32_bf16 v[10:13], v[162:165], v[210:213], v[10:13]
	v_mfma_f32_16x16x32_bf16 v[6:9], v[162:165], v[202:205], v[6:9]
	v_mfma_f32_16x16x32_bf16 v[6:9], v[158:161], v[198:201], v[6:9]
	v_mfma_f32_16x16x32_bf16 v[2:5], v[158:161], v[190:193], v[2:5]
	v_mfma_f32_16x16x32_bf16 v[2:5], v[162:165], v[194:197], v[2:5]
	v_mfma_f32_16x16x32_bf16 v[14:17], v[162:165], v[186:189], v[14:17]
	v_mfma_f32_16x16x32_bf16 v[14:17], v[158:161], v[182:185], v[14:17]
	v_mfma_f32_16x16x32_bf16 v[98:101], v[166:169], v[182:185], v[98:101]
	v_mfma_f32_16x16x32_bf16 v[98:101], v[170:173], v[186:189], v[98:101]
	v_mfma_f32_16x16x32_bf16 v[82:85], v[170:173], v[194:197], v[82:85]
	v_mfma_f32_16x16x32_bf16 v[82:85], v[166:169], v[190:193], v[82:85]
	v_mfma_f32_16x16x32_bf16 v[86:89], v[166:169], v[198:201], v[86:89]
	v_mfma_f32_16x16x32_bf16 v[86:89], v[170:173], v[202:205], v[86:89]
	v_mfma_f32_16x16x32_bf16 v[94:97], v[170:173], v[210:213], v[94:97]
	v_mfma_f32_16x16x32_bf16 v[94:97], v[166:169], v[206:209], v[94:97]
	v_mfma_f32_16x16x32_bf16 v[30:33], v[174:177], v[206:209], v[30:33]
	v_mfma_f32_16x16x32_bf16 v[30:33], v[178:181], v[210:213], v[30:33]
	v_mfma_f32_16x16x32_bf16 v[22:25], v[178:181], v[202:205], v[22:25]
	v_mfma_f32_16x16x32_bf16 v[22:25], v[174:177], v[198:201], v[22:25]
	v_mfma_f32_16x16x32_bf16 v[18:21], v[174:177], v[190:193], v[18:21]
	v_mfma_f32_16x16x32_bf16 v[18:21], v[178:181], v[194:197], v[18:21]
	v_mfma_f32_16x16x32_bf16 v[34:37], v[178:181], v[186:189], v[34:37]
	v_mfma_f32_16x16x32_bf16 v[34:37], v[174:177], v[182:185], v[34:37]
	s_barrier
	s_add_i32 s50, s78, s15
	v_lshl_add_u64 v[214:215], v[214:215], 0, s[8:9]
	s_mov_b32 m0, s50
	ds_read_b128 v[182:185], v149 offset:49152
	ds_read_b128 v[186:189], v149 offset:50176
	ds_read_b128 v[190:193], v149 offset:51200
	ds_read_b128 v[194:197], v149 offset:52224
	ds_read_b128 v[198:201], v149 offset:53248
	ds_read_b128 v[202:205], v149 offset:54272
	ds_read_b128 v[206:209], v149 offset:55296
	ds_read_b128 v[210:213], v149 offset:56320
	global_load_lds_dwordx4 v[214:215], off
	s_add_i32 m0, s50, 0x2000
	s_add_u32 s50, s52, 0x40080
	v_lshl_add_u64 v[214:215], v[216:217], 0, s[8:9]
	s_addc_u32 s51, s53, 0
	s_add_i32 s52, s79, s15
	global_load_lds_dwordx4 v[214:215], off
	v_lshl_add_u64 v[214:215], s[50:51], 0, v[228:229]
	s_mov_b32 m0, s52
	s_nop 0
	global_load_lds_dwordx4 v[214:215], off
	v_lshl_add_u64 v[214:215], s[50:51], 0, v[232:233]
	s_add_i32 m0, s52, 0x2000
	s_nop 0
	global_load_lds_dwordx4 v[214:215], off
	v_lshl_add_u64 v[214:215], v[218:219], 0, s[8:9]
	s_mov_b32 m0, s68
	s_nop 0
	global_load_lds_dwordx4 v[214:215], off
	v_lshl_add_u64 v[214:215], v[220:221], 0, s[8:9]
	s_mov_b32 m0, s69
	s_nop 0
	global_load_lds_dwordx4 v[214:215], off
	s_waitcnt vmcnt(8)
	s_waitcnt lgkmcnt(0)
	s_barrier
	v_mfma_f32_16x16x32_bf16 v[90:93], v[150:153], v[182:185], v[90:93]
	v_mfma_f32_16x16x32_bf16 v[90:93], v[154:157], v[186:189], v[90:93]
	v_mfma_f32_16x16x32_bf16 v[102:105], v[154:157], v[194:197], v[102:105]
	v_mfma_f32_16x16x32_bf16 v[102:105], v[150:153], v[190:193], v[102:105]
	v_mfma_f32_16x16x32_bf16 v[106:109], v[150:153], v[198:201], v[106:109]
	v_mfma_f32_16x16x32_bf16 v[106:109], v[154:157], v[202:205], v[106:109]
	v_mfma_f32_16x16x32_bf16 v[110:113], v[154:157], v[210:213], v[110:113]
	v_mfma_f32_16x16x32_bf16 v[110:113], v[150:153], v[206:209], v[110:113]
	v_mfma_f32_16x16x32_bf16 v[46:49], v[158:161], v[206:209], v[46:49]
	v_mfma_f32_16x16x32_bf16 v[46:49], v[162:165], v[210:213], v[46:49]
	v_mfma_f32_16x16x32_bf16 v[42:45], v[162:165], v[202:205], v[42:45]
	v_mfma_f32_16x16x32_bf16 v[42:45], v[158:161], v[198:201], v[42:45]
	v_mfma_f32_16x16x32_bf16 v[38:41], v[158:161], v[190:193], v[38:41]
	v_mfma_f32_16x16x32_bf16 v[38:41], v[162:165], v[194:197], v[38:41]
	v_mfma_f32_16x16x32_bf16 v[26:29], v[162:165], v[186:189], v[26:29]
	v_mfma_f32_16x16x32_bf16 v[26:29], v[158:161], v[182:185], v[26:29]
	v_mfma_f32_16x16x32_bf16 v[114:117], v[166:169], v[182:185], v[114:117]
	v_mfma_f32_16x16x32_bf16 v[114:117], v[170:173], v[186:189], v[114:117]
	v_mfma_f32_16x16x32_bf16 v[118:121], v[170:173], v[194:197], v[118:121]
	v_mfma_f32_16x16x32_bf16 v[118:121], v[166:169], v[190:193], v[118:121]
	v_mfma_f32_16x16x32_bf16 v[122:125], v[166:169], v[198:201], v[122:125]
	v_mfma_f32_16x16x32_bf16 v[122:125], v[170:173], v[202:205], v[122:125]
	v_mfma_f32_16x16x32_bf16 v[126:129], v[170:173], v[210:213], v[126:129]
	v_mfma_f32_16x16x32_bf16 v[126:129], v[166:169], v[206:209], v[126:129]
	v_mfma_f32_16x16x32_bf16 v[62:65], v[174:177], v[206:209], v[62:65]
	v_mfma_f32_16x16x32_bf16 v[62:65], v[178:181], v[210:213], v[62:65]
	v_mfma_f32_16x16x32_bf16 v[58:61], v[178:181], v[202:205], v[58:61]
	v_mfma_f32_16x16x32_bf16 v[58:61], v[174:177], v[198:201], v[58:61]
	v_mfma_f32_16x16x32_bf16 v[54:57], v[174:177], v[190:193], v[54:57]
	v_mfma_f32_16x16x32_bf16 v[54:57], v[178:181], v[194:197], v[54:57]
	v_mfma_f32_16x16x32_bf16 v[50:53], v[178:181], v[186:189], v[50:53]
	v_mfma_f32_16x16x32_bf16 v[50:53], v[174:177], v[182:185], v[50:53]
	s_barrier
	s_add_u32 s34, s34, 0x100
	s_addc_u32 s35, s35, 0
	s_add_u32 s21, s21, 0x100
	s_addc_u32 s23, s23, 0
	s_cmp_ge_i32 s77, s66
	s_mov_b32 s52, s77
	s_cbranch_scc0 .LBB0_872

.LBB0_1009:
	v_add_u32_e32 v0, s64, v187
	ds_read_b128 v[130:133], v0
	ds_read_b128 v[134:137], v0 offset:1024
	ds_read_b128 v[138:141], v0 offset:2048
	ds_read_b128 v[142:145], v0 offset:3072
	v_add_u32_e32 v0, s65, v187
	ds_read_b128 v[146:149], v0
	ds_read_b128 v[150:153], v0 offset:1024
	ds_read_b128 v[178:181], v0 offset:2048
	ds_read_b128 v[182:185], v0 offset:3072
	s_add_i32 s35, s42, 2
	s_add_u32 s43, s36, 0x3fc000
	s_addc_u32 s44, s37, 0
	s_cmp_eq_u32 s61, s42
	s_cselect_b32 s46, s28, s43
	s_cselect_b32 s47, s29, s44
	s_cselect_b32 s44, s30, s11
	s_cselect_b32 s45, s31, s27
	s_add_u32 s42, s46, 0x400000
	s_addc_u32 s43, s47, 0
	v_lshl_add_u64 v[0:1], s[36:37], 0, v[168:169]
	s_add_i32 m0, s51, 0xc000
	ds_read_b128 v[220:223], v215
	ds_read_b128 v[224:227], v215 offset:1024
	ds_read_b128 v[228:231], v215 offset:2048
	ds_read_b128 v[232:235], v215 offset:3072
	ds_read_b128 v[236:239], v215 offset:4096
	ds_read_b128 v[240:243], v215 offset:5120
	ds_read_b128 v[244:247], v215 offset:6144
	ds_read_b128 v[248:251], v215 offset:7168
	global_load_lds_dwordx4 v[0:1], off
	v_lshl_add_u64 v[0:1], s[36:37], 0, v[170:171]
	s_add_i32 m0, s51, 0xe000
	s_nop 0
	global_load_lds_dwordx4 v[0:1], off
	s_waitcnt vmcnt(8)
	s_waitcnt lgkmcnt(0)
	s_barrier
	v_mfma_f32_16x16x32_bf16 v[114:117], v[130:133], v[220:223], v[114:117]
	v_mfma_f32_16x16x32_bf16 v[114:117], v[134:137], v[224:227], v[114:117]
	v_mfma_f32_16x16x32_bf16 v[110:113], v[134:137], v[232:235], v[110:113]
	v_mfma_f32_16x16x32_bf16 v[110:113], v[130:133], v[228:231], v[110:113]
	v_mfma_f32_16x16x32_bf16 v[94:97], v[130:133], v[236:239], v[94:97]
	v_mfma_f32_16x16x32_bf16 v[94:97], v[134:137], v[240:243], v[94:97]
	v_mfma_f32_16x16x32_bf16 v[78:81], v[134:137], v[248:251], v[78:81]
	v_mfma_f32_16x16x32_bf16 v[78:81], v[130:133], v[244:247], v[78:81]
	v_mfma_f32_16x16x32_bf16 v[70:73], v[138:141], v[244:247], v[70:73]
	v_mfma_f32_16x16x32_bf16 v[70:73], v[142:145], v[248:251], v[70:73]
	v_mfma_f32_16x16x32_bf16 v[86:89], v[142:145], v[240:243], v[86:89]
	v_mfma_f32_16x16x32_bf16 v[86:89], v[138:141], v[236:239], v[86:89]
	v_mfma_f32_16x16x32_bf16 v[102:105], v[138:141], v[228:231], v[102:105]
	v_mfma_f32_16x16x32_bf16 v[102:105], v[142:145], v[232:235], v[102:105]
	v_mfma_f32_16x16x32_bf16 v[118:121], v[142:145], v[224:227], v[118:121]
	v_mfma_f32_16x16x32_bf16 v[118:121], v[138:141], v[220:223], v[118:121]
	v_mfma_f32_16x16x32_bf16 v[126:129], v[146:149], v[220:223], v[126:129]
	v_mfma_f32_16x16x32_bf16 v[126:129], v[150:153], v[224:227], v[126:129]
	v_mfma_f32_16x16x32_bf16 v[106:109], v[150:153], v[232:235], v[106:109]
	v_mfma_f32_16x16x32_bf16 v[106:109], v[146:149], v[228:231], v[106:109]
	v_mfma_f32_16x16x32_bf16 v[90:93], v[146:149], v[236:239], v[90:93]
	v_mfma_f32_16x16x32_bf16 v[90:93], v[150:153], v[240:243], v[90:93]
	v_mfma_f32_16x16x32_bf16 v[74:77], v[150:153], v[248:251], v[74:77]
	v_mfma_f32_16x16x32_bf16 v[74:77], v[146:149], v[244:247], v[74:77]
	v_mfma_f32_16x16x32_bf16 v[66:69], v[178:181], v[244:247], v[66:69]
	v_mfma_f32_16x16x32_bf16 v[66:69], v[182:185], v[248:251], v[66:69]
	v_mfma_f32_16x16x32_bf16 v[82:85], v[182:185], v[240:243], v[82:85]
	v_mfma_f32_16x16x32_bf16 v[82:85], v[178:181], v[236:239], v[82:85]
	v_mfma_f32_16x16x32_bf16 v[98:101], v[178:181], v[228:231], v[98:101]
	v_mfma_f32_16x16x32_bf16 v[98:101], v[182:185], v[232:235], v[98:101]
	v_mfma_f32_16x16x32_bf16 v[122:125], v[182:185], v[224:227], v[122:125]
	v_mfma_f32_16x16x32_bf16 v[122:125], v[178:181], v[220:223], v[122:125]
	s_barrier
	s_add_i32 s69, s64, s49
	v_lshl_add_u64 v[252:253], s[44:45], 0, v[156:157]
	s_mov_b32 m0, s69
	ds_read_b128 v[220:223], v215 offset:16384
	ds_read_b128 v[224:227], v215 offset:17408
	ds_read_b128 v[228:231], v215 offset:18432
	ds_read_b128 v[232:235], v215 offset:19456
	ds_read_b128 v[236:239], v215 offset:20480
	ds_read_b128 v[240:243], v215 offset:21504
	ds_read_b128 v[244:247], v215 offset:22528
	ds_read_b128 v[248:251], v215 offset:23552
	global_load_lds_dwordx4 v[252:253], off
	s_add_i32 m0, s69, 0x2000
	s_add_u32 s70, s44, 0xb0000
	v_lshl_add_u64 v[172:173], s[44:45], 0, v[160:161]
	s_addc_u32 s71, s45, 0
	s_add_i32 s69, s65, s49
	global_load_lds_dwordx4 v[172:173], off
	v_lshl_add_u64 v[0:1], s[70:71], 0, v[156:157]
	s_mov_b32 m0, s69
	s_nop 0
	global_load_lds_dwordx4 v[0:1], off
	v_lshl_add_u64 v[0:1], s[70:71], 0, v[160:161]
	s_add_i32 m0, s69, 0x2000
	s_nop 0
	global_load_lds_dwordx4 v[0:1], off
	v_lshl_add_u64 v[0:1], s[46:47], 0, v[154:155]
	s_mov_b32 m0, s51
	s_nop 0
	global_load_lds_dwordx4 v[0:1], off
	v_lshl_add_u64 v[0:1], s[46:47], 0, v[158:159]
	s_mov_b32 m0, s52
	s_nop 0
	global_load_lds_dwordx4 v[0:1], off
	s_waitcnt vmcnt(8)
	s_waitcnt lgkmcnt(0)
	s_barrier
	v_mfma_f32_16x16x32_bf16 v[50:53], v[130:133], v[220:223], v[50:53]
	v_mfma_f32_16x16x32_bf16 v[54:57], v[138:141], v[220:223], v[54:57]
	v_mfma_f32_16x16x32_bf16 v[46:49], v[130:133], v[228:231], v[46:49]
	v_mfma_f32_16x16x32_bf16 v[38:41], v[138:141], v[228:231], v[38:41]
	v_mfma_f32_16x16x32_bf16 v[30:33], v[130:133], v[236:239], v[30:33]
	v_mfma_f32_16x16x32_bf16 v[22:25], v[138:141], v[236:239], v[22:25]
	v_mfma_f32_16x16x32_bf16 v[14:17], v[130:133], v[244:247], v[14:17]
	v_mfma_f32_16x16x32_bf16 v[6:9], v[138:141], v[244:247], v[6:9]
	v_mfma_f32_16x16x32_bf16 v[50:53], v[134:137], v[224:227], v[50:53]
	v_mfma_f32_16x16x32_bf16 v[54:57], v[142:145], v[224:227], v[54:57]
	v_mfma_f32_16x16x32_bf16 v[46:49], v[134:137], v[232:235], v[46:49]
	v_mfma_f32_16x16x32_bf16 v[38:41], v[142:145], v[232:235], v[38:41]
	v_mfma_f32_16x16x32_bf16 v[30:33], v[134:137], v[240:243], v[30:33]
	v_mfma_f32_16x16x32_bf16 v[22:25], v[142:145], v[240:243], v[22:25]
	v_mfma_f32_16x16x32_bf16 v[14:17], v[134:137], v[248:251], v[14:17]
	v_mfma_f32_16x16x32_bf16 v[6:9], v[142:145], v[248:251], v[6:9]
	v_mfma_f32_16x16x32_bf16 v[62:65], v[146:149], v[220:223], v[62:65]
	v_mfma_f32_16x16x32_bf16 v[58:61], v[178:181], v[220:223], v[58:61]
	v_mfma_f32_16x16x32_bf16 v[42:45], v[146:149], v[228:231], v[42:45]
	v_mfma_f32_16x16x32_bf16 v[34:37], v[178:181], v[228:231], v[34:37]
	v_mfma_f32_16x16x32_bf16 v[26:29], v[146:149], v[236:239], v[26:29]
	v_mfma_f32_16x16x32_bf16 v[18:21], v[178:181], v[236:239], v[18:21]
	v_mfma_f32_16x16x32_bf16 v[10:13], v[146:149], v[244:247], v[10:13]
	v_mfma_f32_16x16x32_bf16 v[0:3], v[178:181], v[244:247], v[2:5]
	v_mfma_f32_16x16x32_bf16 v[62:65], v[150:153], v[224:227], v[62:65]
	v_mfma_f32_16x16x32_bf16 v[58:61], v[182:185], v[224:227], v[58:61]
	v_mfma_f32_16x16x32_bf16 v[42:45], v[150:153], v[232:235], v[42:45]
	v_mfma_f32_16x16x32_bf16 v[34:37], v[182:185], v[232:235], v[34:37]
	v_mfma_f32_16x16x32_bf16 v[26:29], v[150:153], v[240:243], v[26:29]
	v_mfma_f32_16x16x32_bf16 v[18:21], v[182:185], v[240:243], v[18:21]
	v_mfma_f32_16x16x32_bf16 v[10:13], v[150:153], v[248:251], v[10:13]
	v_mfma_f32_16x16x32_bf16 v[0:3], v[182:185], v[248:251], v[0:3]
	s_barrier
	s_add_i32 s69, 0, 0x18000
	v_add_u32_e32 v4, s69, v187
	s_add_i32 s70, 0, 0x1c000
	ds_read_b128 v[130:133], v4
	ds_read_b128 v[134:137], v4 offset:1024
	ds_read_b128 v[138:141], v4 offset:2048
	ds_read_b128 v[142:145], v4 offset:3072
	v_add_u32_e32 v4, s70, v187
	ds_read_b128 v[146:149], v4
	ds_read_b128 v[150:153], v4 offset:1024
	ds_read_b128 v[178:181], v4 offset:2048
	ds_read_b128 v[182:185], v4 offset:3072
	s_add_u32 s46, s46, 0x4000
	s_addc_u32 s47, s47, 0
	s_mov_b32 m0, s53
	v_lshl_add_u64 v[4:5], s[46:47], 0, v[154:155]
	ds_read_b128 v[220:223], v215 offset:32768
	ds_read_b128 v[224:227], v215 offset:33792
	ds_read_b128 v[228:231], v215 offset:34816
	ds_read_b128 v[232:235], v215 offset:35840
	ds_read_b128 v[236:239], v215 offset:36864
	ds_read_b128 v[240:243], v215 offset:37888
	ds_read_b128 v[244:247], v215 offset:38912
	ds_read_b128 v[248:251], v215 offset:39936
	global_load_lds_dwordx4 v[4:5], off
	v_lshl_add_u64 v[4:5], s[46:47], 0, v[158:159]
	s_mov_b32 m0, s54
	s_nop 0
	global_load_lds_dwordx4 v[4:5], off
	s_waitcnt vmcnt(8)
	s_waitcnt lgkmcnt(0)
	s_barrier
	v_mfma_f32_16x16x32_bf16 v[114:117], v[130:133], v[220:223], v[114:117]
	v_mfma_f32_16x16x32_bf16 v[114:117], v[134:137], v[224:227], v[114:117]
	v_mfma_f32_16x16x32_bf16 v[110:113], v[134:137], v[232:235], v[110:113]
	v_mfma_f32_16x16x32_bf16 v[110:113], v[130:133], v[228:231], v[110:113]
	v_mfma_f32_16x16x32_bf16 v[94:97], v[130:133], v[236:239], v[94:97]
	v_mfma_f32_16x16x32_bf16 v[94:97], v[134:137], v[240:243], v[94:97]
	v_mfma_f32_16x16x32_bf16 v[78:81], v[134:137], v[248:251], v[78:81]
	v_mfma_f32_16x16x32_bf16 v[78:81], v[130:133], v[244:247], v[78:81]
	v_mfma_f32_16x16x32_bf16 v[70:73], v[138:141], v[244:247], v[70:73]
	v_mfma_f32_16x16x32_bf16 v[70:73], v[142:145], v[248:251], v[70:73]
	v_mfma_f32_16x16x32_bf16 v[86:89], v[142:145], v[240:243], v[86:89]
	v_mfma_f32_16x16x32_bf16 v[86:89], v[138:141], v[236:239], v[86:89]
	v_mfma_f32_16x16x32_bf16 v[102:105], v[138:141], v[228:231], v[102:105]
	v_mfma_f32_16x16x32_bf16 v[102:105], v[142:145], v[232:235], v[102:105]
	v_mfma_f32_16x16x32_bf16 v[118:121], v[142:145], v[224:227], v[118:121]
	v_mfma_f32_16x16x32_bf16 v[118:121], v[138:141], v[220:223], v[118:121]
	v_mfma_f32_16x16x32_bf16 v[126:129], v[146:149], v[220:223], v[126:129]
	v_mfma_f32_16x16x32_bf16 v[126:129], v[150:153], v[224:227], v[126:129]
	v_mfma_f32_16x16x32_bf16 v[106:109], v[150:153], v[232:235], v[106:109]
	v_mfma_f32_16x16x32_bf16 v[106:109], v[146:149], v[228:231], v[106:109]
	v_mfma_f32_16x16x32_bf16 v[90:93], v[146:149], v[236:239], v[90:93]
	v_mfma_f32_16x16x32_bf16 v[90:93], v[150:153], v[240:243], v[90:93]
	v_mfma_f32_16x16x32_bf16 v[74:77], v[150:153], v[248:251], v[74:77]
	v_mfma_f32_16x16x32_bf16 v[74:77], v[146:149], v[244:247], v[74:77]
	v_mfma_f32_16x16x32_bf16 v[66:69], v[178:181], v[244:247], v[66:69]
	v_mfma_f32_16x16x32_bf16 v[66:69], v[182:185], v[248:251], v[66:69]
	v_mfma_f32_16x16x32_bf16 v[82:85], v[182:185], v[240:243], v[82:85]
	v_mfma_f32_16x16x32_bf16 v[82:85], v[178:181], v[236:239], v[82:85]
	v_mfma_f32_16x16x32_bf16 v[98:101], v[178:181], v[228:231], v[98:101]
	v_mfma_f32_16x16x32_bf16 v[98:101], v[182:185], v[232:235], v[98:101]
	v_mfma_f32_16x16x32_bf16 v[122:125], v[182:185], v[224:227], v[122:125]
	v_mfma_f32_16x16x32_bf16 v[122:125], v[178:181], v[220:223], v[122:125]
	s_barrier
	s_add_i32 s46, s69, s49
	v_lshl_add_u64 v[4:5], v[252:253], 0, s[18:19]
	s_mov_b32 m0, s46
	ds_read_b128 v[220:223], v215 offset:49152
	ds_read_b128 v[224:227], v215 offset:50176
	ds_read_b128 v[228:231], v215 offset:51200
	ds_read_b128 v[232:235], v215 offset:52224
	ds_read_b128 v[236:239], v215 offset:53248
	ds_read_b128 v[240:243], v215 offset:54272
	ds_read_b128 v[244:247], v215 offset:55296
	ds_read_b128 v[248:251], v215 offset:56320
	global_load_lds_dwordx4 v[4:5], off
	s_add_i32 m0, s46, 0x2000
	s_add_u32 s44, s44, 0xb0080
	v_lshl_add_u64 v[4:5], v[172:173], 0, s[18:19]
	s_addc_u32 s45, s45, 0
	s_add_i32 s46, s70, s49
	global_load_lds_dwordx4 v[4:5], off
	v_lshl_add_u64 v[4:5], s[44:45], 0, v[156:157]
	s_mov_b32 m0, s46
	s_nop 0
	global_load_lds_dwordx4 v[4:5], off
	v_lshl_add_u64 v[4:5], s[44:45], 0, v[160:161]
	s_add_i32 m0, s46, 0x2000
	s_nop 0
	global_load_lds_dwordx4 v[4:5], off
	v_lshl_add_u64 v[4:5], s[42:43], 0, v[154:155]
	s_mov_b32 m0, s59
	s_nop 0
	global_load_lds_dwordx4 v[4:5], off
	v_lshl_add_u64 v[4:5], s[42:43], 0, v[158:159]
	s_mov_b32 m0, s60
	s_nop 0
	global_load_lds_dwordx4 v[4:5], off
	s_waitcnt vmcnt(8)
	s_waitcnt lgkmcnt(0)
	s_barrier
	v_mfma_f32_16x16x32_bf16 v[50:53], v[130:133], v[220:223], v[50:53]
	v_mfma_f32_16x16x32_bf16 v[54:57], v[138:141], v[220:223], v[54:57]
	v_mfma_f32_16x16x32_bf16 v[46:49], v[130:133], v[228:231], v[46:49]
	v_mfma_f32_16x16x32_bf16 v[38:41], v[138:141], v[228:231], v[38:41]
	v_mfma_f32_16x16x32_bf16 v[30:33], v[130:133], v[236:239], v[30:33]
	v_mfma_f32_16x16x32_bf16 v[22:25], v[138:141], v[236:239], v[22:25]
	v_mfma_f32_16x16x32_bf16 v[14:17], v[130:133], v[244:247], v[14:17]
	v_mfma_f32_16x16x32_bf16 v[4:7], v[138:141], v[244:247], v[6:9]
	v_mfma_f32_16x16x32_bf16 v[50:53], v[134:137], v[224:227], v[50:53]
	v_mfma_f32_16x16x32_bf16 v[54:57], v[142:145], v[224:227], v[54:57]
	v_mfma_f32_16x16x32_bf16 v[46:49], v[134:137], v[232:235], v[46:49]
	v_mfma_f32_16x16x32_bf16 v[38:41], v[142:145], v[232:235], v[38:41]
	v_mfma_f32_16x16x32_bf16 v[30:33], v[134:137], v[240:243], v[30:33]
	v_mfma_f32_16x16x32_bf16 v[22:25], v[142:145], v[240:243], v[22:25]
	v_mfma_f32_16x16x32_bf16 v[14:17], v[134:137], v[248:251], v[14:17]
	v_mfma_f32_16x16x32_bf16 v[6:9], v[142:145], v[248:251], v[4:7]
	v_mfma_f32_16x16x32_bf16 v[62:65], v[146:149], v[220:223], v[62:65]
	v_mfma_f32_16x16x32_bf16 v[58:61], v[178:181], v[220:223], v[58:61]
	v_mfma_f32_16x16x32_bf16 v[42:45], v[146:149], v[228:231], v[42:45]
	v_mfma_f32_16x16x32_bf16 v[34:37], v[178:181], v[228:231], v[34:37]
	v_mfma_f32_16x16x32_bf16 v[26:29], v[146:149], v[236:239], v[26:29]
	v_mfma_f32_16x16x32_bf16 v[18:21], v[178:181], v[236:239], v[18:21]
	v_mfma_f32_16x16x32_bf16 v[10:13], v[146:149], v[244:247], v[10:13]
	v_mfma_f32_16x16x32_bf16 v[0:3], v[178:181], v[244:247], v[0:3]
	v_mfma_f32_16x16x32_bf16 v[62:65], v[150:153], v[224:227], v[62:65]
	v_mfma_f32_16x16x32_bf16 v[58:61], v[182:185], v[224:227], v[58:61]
	v_mfma_f32_16x16x32_bf16 v[42:45], v[150:153], v[232:235], v[42:45]
	v_mfma_f32_16x16x32_bf16 v[34:37], v[182:185], v[232:235], v[34:37]
	v_mfma_f32_16x16x32_bf16 v[26:29], v[150:153], v[240:243], v[26:29]
	v_mfma_f32_16x16x32_bf16 v[18:21], v[182:185], v[240:243], v[18:21]
	v_mfma_f32_16x16x32_bf16 v[10:13], v[150:153], v[248:251], v[10:13]
	v_mfma_f32_16x16x32_bf16 v[2:5], v[182:185], v[248:251], v[0:3]
	s_barrier
	s_add_u32 s11, s11, 0x100
	s_addc_u32 s27, s27, 0
	s_add_u32 s36, s36, 0x800000
	s_addc_u32 s37, s37, 0
	s_cmp_ge_i32 s35, s58
	s_mov_b32 s42, s35
	s_cbranch_scc0 .LBB0_1009
	v_mov_b64_e32 v[234:235], v[174:175]
	s_and_b64 vcc, exec, s[22:23]
	s_cbranch_vccnz .LBB0_980
	s_branch .LBB0_981
